# scan: v block-load + DPP row broadcast (3 loads per step)
# speedup vs baseline: 1.0091x; 1.0091x over previous
; #define RW_LOAD(slot, step) do { const size_t ro_ = (size_t)row_of(step) * RWW; \
;       s_ok[slot] = *(const h16x8*)((p_rec + ro_ * 3) + urec); s_b[slot] = *(const h16x4*)((p_rec + ro_ * 3) + urec + 8); \
;       s_kr[slot] = *(const h16x8*)((p_sh + ro_ * 2) + ush); s_v[slot] = (p_v + ro_)[uvoff]; } while (0)
; template <int VAR>
; __device__ __forceinline__ void ph_rw_scan(const Params& P) {
;     ...
;     const int rg = wu % 16, hh = (wu / 16) % RW_H, b = (wu / (16 * RW_H)) % BATCH, dir = wu / (16 * RW_H * BATCH);
;     const int vrow = rg * 4 + rl;
;     ...
;     const unsigned g_ = (unsigned)(hh * 16 + q);
;     const unsigned uvoff = (unsigned)(hh * 64 + vrow), urec = g_ * 12u, ush = g_ * 8u;
;     h16x8 s_ok[RW_U], s_kr[RW_U]; h16x4 s_b[RW_U]; h16 s_v[RW_U];
;     auto row_of = [&](int step) -> int {
;       if (step < CTX_LEN) return NL + b * CTX_LEN + (dir == 0 ? step : CTX_LEN - 1 - step);
;       const int s = step - CTX_LEN; return b * SEQ + (dir == 0 ? s : SEQ - 1 - s);
;     };
;     ...
; #pragma unroll
;     for (int uu = 0; uu < RW_U; ++uu) RW_LOAD(uu, uu);
.Lscan_unit:
	s_and_b32 s26, s0, 15
	s_bfe_u32 s27, s0, 0x40004
	s_bfe_u32 s28, s0, 0x10008
	s_lshr_b32 s29, s0, 9
	s_lshl_b32 s30, s27, 4
	v_add_u32_e32 v4, s30, v2
	v_mul_u32_u24_e32 v5, 24, v4
	v_lshlrev_b32_e32 v6, 4, v4
	s_lshl_b32 s30, s27, 6
	s_lshl_b32 s31, s26, 2
	s_add_u32 s30, s30, s31
	v_add_u32_e32 v7, s30, v3
	v_lshlrev_b32_e32 v7, 1, v7
	s_cmp_lg_u32 s29, 0
	s_cbranch_scc1 .Lscan_dir1
	v_mov_b32_e32 v52, v5
	v_add_u32_e32 v53, 0x1800, v5
	v_add_u32_e32 v54, 0x3000, v5
	v_add_u32_e32 v55, 0x4800, v5
	v_add_u32_e32 v56, 0x6000, v5
	v_add_u32_e32 v57, 0x7800, v5
	v_add_u32_e32 v58, 0x9000, v5
	v_add_u32_e32 v59, 0xa800, v5
	v_add_u32_e32 v60, 0xc000, v5
	v_add_u32_e32 v61, 0xd800, v5
	v_add_u32_e32 v62, 0xf000, v5
	v_add_u32_e32 v63, 0x10800, v5
	v_add_u32_e32 v64, 0x12000, v5
	v_add_u32_e32 v65, 0x13800, v5
	v_add_u32_e32 v66, 0x15000, v5
	v_add_u32_e32 v67, 0x16800, v5
	v_add_u32_e32 v68, 0x1000, v6
	v_add_u32_e32 v69, 0x3000, v6
	v_add_u32_e32 v70, 0x5000, v6
	v_add_u32_e32 v71, 0x7000, v6
	v_add_u32_e32 v72, 0x9000, v6
	v_add_u32_e32 v73, 0xb000, v6
	v_add_u32_e32 v74, 0xd000, v6
	v_add_u32_e32 v75, 0xf000, v6
	v_add_u32_e32 v76, 0x1000, v7
	v_add_u32_e32 v77, 0x3000, v7
	v_add_u32_e32 v78, 0x5000, v7
	v_add_u32_e32 v79, 0x7000, v7
	v_lshlrev_b32_e32 v80, 11, v2
	v_add_u32_e32 v80, v80, v7
	s_lshl_b32 s30, s28, 8
	s_add_u32 s30, s30, 0x8000
	s_lshl_b32 s31, s28, 14
	s_mul_i32 s1, s30, 0x1800
	s_add_u32 s6, s4, s1
	s_addc_u32 s7, s5, 0
	s_add_u32 s6, s6, 0x23614000
	s_addc_u32 s7, s7, 0
	s_mul_i32 s1, s30, 0x1000
	s_add_u32 s8, s4, s1
	s_addc_u32 s9, s5, 0
	s_add_u32 s8, s8, 0xbe4c000
	s_addc_u32 s9, s9, 0
	s_mul_i32 s1, s30, 0x800
	s_add_u32 s10, s4, s1
	s_addc_u32 s11, s5, 0
	s_add_u32 s10, s10, 0x3bc14000
	s_addc_u32 s11, s11, 0
	s_mul_i32 s1, s31, 0x1800
	s_add_u32 s14, s4, s1
	s_addc_u32 s15, s5, 0
	s_add_u32 s14, s14, 0x23614000
	s_addc_u32 s15, s15, 0
	s_mul_i32 s1, s31, 0x1000
	s_add_u32 s16, s4, s1
	s_addc_u32 s17, s5, 0
	s_add_u32 s16, s16, 0xbe4c000
	s_addc_u32 s17, s17, 0
	s_mul_i32 s1, s31, 0x800
	s_add_u32 s18, s4, s1
	s_addc_u32 s19, s5, 0
	s_add_u32 s18, s18, 0x3bc14000
	s_addc_u32 s19, s19, 0
	s_mul_i32 s1, s31, 0x800
	s_add_u32 s12, s4, s1
	s_addc_u32 s13, s5, 0
	s_add_u32 s12, s12, 0x160cc000
	s_addc_u32 s13, s13, 0
	v_mov_b32_e32 v10, 0
	v_mov_b32_e32 v11, 0
	v_mov_b32_e32 v12, 0
	v_mov_b32_e32 v13, 0
	global_load_ushort v36, v80, s[10:11]
	global_load_dwordx4 v[84:87], v52, s[6:7]
	global_load_dwordx2 v[88:89], v52, s[6:7] offset:16
	global_load_dwordx4 v[90:93], v68, s[8:9] offset:-4096
	global_load_dwordx4 v[94:97], v53, s[6:7]
	global_load_dwordx2 v[98:99], v53, s[6:7] offset:16
	global_load_dwordx4 v[100:103], v68, s[8:9]
	global_load_dwordx4 v[104:107], v54, s[6:7]
	global_load_dwordx2 v[108:109], v54, s[6:7] offset:16
	global_load_dwordx4 v[110:113], v69, s[8:9] offset:-4096
	global_load_dwordx4 v[114:117], v55, s[6:7]
	global_load_dwordx2 v[118:119], v55, s[6:7] offset:16
	global_load_dwordx4 v[120:123], v69, s[8:9]
	global_load_dwordx4 v[124:127], v56, s[6:7]
	global_load_dwordx2 v[128:129], v56, s[6:7] offset:16
	global_load_dwordx4 v[130:133], v70, s[8:9] offset:-4096
	global_load_dwordx4 v[134:137], v57, s[6:7]
	global_load_dwordx2 v[138:139], v57, s[6:7] offset:16
	global_load_dwordx4 v[140:143], v70, s[8:9]
	global_load_dwordx4 v[144:147], v58, s[6:7]
	global_load_dwordx2 v[148:149], v58, s[6:7] offset:16
	global_load_dwordx4 v[150:153], v71, s[8:9] offset:-4096
	global_load_dwordx4 v[154:157], v59, s[6:7]
	global_load_dwordx2 v[158:159], v59, s[6:7] offset:16
	global_load_dwordx4 v[160:163], v71, s[8:9]
	global_load_dwordx4 v[164:167], v60, s[6:7]
	global_load_dwordx2 v[168:169], v60, s[6:7] offset:16
	global_load_dwordx4 v[170:173], v72, s[8:9] offset:-4096
	global_load_dwordx4 v[174:177], v61, s[6:7]
	global_load_dwordx2 v[178:179], v61, s[6:7] offset:16
	global_load_dwordx4 v[180:183], v72, s[8:9]
	global_load_dwordx4 v[184:187], v62, s[6:7]
	global_load_dwordx2 v[188:189], v62, s[6:7] offset:16
	global_load_dwordx4 v[190:193], v73, s[8:9] offset:-4096
	global_load_dwordx4 v[194:197], v63, s[6:7]
	global_load_dwordx2 v[198:199], v63, s[6:7] offset:16
	global_load_dwordx4 v[200:203], v73, s[8:9]
	global_load_dwordx4 v[204:207], v64, s[6:7]
	global_load_dwordx2 v[208:209], v64, s[6:7] offset:16
	global_load_dwordx4 v[210:213], v74, s[8:9] offset:-4096
	global_load_dwordx4 v[214:217], v65, s[6:7]
	global_load_dwordx2 v[218:219], v65, s[6:7] offset:16
	global_load_dwordx4 v[220:223], v74, s[8:9]
	global_load_dwordx4 v[224:227], v66, s[6:7]
	global_load_dwordx2 v[228:229], v66, s[6:7] offset:16
	global_load_dwordx4 v[230:233], v75, s[8:9] offset:-4096
	s_mov_b32 s3, 0
	s_waitcnt vmcnt(42)
; __device__ __forceinline__ float row_sum16(float v) { v += __shfl_xor(v, 1); v += __shfl_xor(v, 2); v += __shfl_xor(v, 4); v += __shfl_xor(v, 8); return v; }
; __device__ __forceinline__ float row_sum16(float v) { v += dppf<0xB1>(v); v += dppf<0x4E>(v); v += dppf<0x124>(v); v += dppf<0x128>(v); return v; }
; #define RW_LOAD(slot, step) do { const size_t ro_ = (size_t)row_of(step) * RWW; \
;       s_ok[slot] = *(const h16x8*)((p_rec + ro_ * 3) + urec); s_b[slot] = *(const h16x4*)((p_rec + ro_ * 3) + urec + 8); \
;       s_kr[slot] = *(const h16x8*)((p_sh + ro_ * 2) + ush); s_v[slot] = (p_v + ro_)[uvoff]; } while (0)
; template <int VAR>
; __device__ __forceinline__ void ph_rw_scan(const Params& P) {
;     ...
;       for (int uu = 0; uu < RW_U; ++uu) {
;         const float vv = (float)s_v[uu];
;         const u32x4 p_ok = __builtin_bit_cast(u32x4, s_ok[uu]), p_kr = __builtin_bit_cast(u32x4, s_kr[uu]);
;         const u32x2 p_bb = __builtin_bit_cast(u32x2, s_b[uu]);
;         const unsigned om0 = p_ok[0], om1 = p_ok[1], kd0 = p_ok[2], kd1 = p_ok[3];
;         const unsigned kk0 = p_kr[0], kk1 = p_kr[1], r0_ = p_kr[2], r1_ = p_kr[3];
;         const unsigned b0_ = p_bb[0], b1_ = p_bb[1];
;         float sa = fmix_lo(S[0], kk0, 0.f); sa = fmix_hi(S[1], kk0, sa);
;         float sb = fmix_lo(S[2], kk1, 0.f); sb = fmix_hi(S[3], kk1, sb);
;         sa = row_sum16(sa + sb);
;         S[0] = fmix_lo(S[0], om0, S[0]); S[1] = fmix_hi(S[1], om0, S[1]); S[2] = fmix_lo(S[2], om1, S[2]); S[3] = fmix_hi(S[3], om1, S[3]);
;         S[0] = fmix_lo(sa, b0_, S[0]); S[1] = fmix_hi(sa, b0_, S[1]); S[2] = fmix_lo(sa, b1_, S[2]); S[3] = fmix_hi(sa, b1_, S[3]);
;         S[0] = fmix_lo(vv, kd0, S[0]); S[1] = fmix_hi(vv, kd0, S[1]); S[2] = fmix_lo(vv, kd1, S[2]); S[3] = fmix_hi(vv, kd1, S[3]);
;         float y = fmix_lo(S[0], r0_, 0.f); y = fmix_hi(S[1], r0_, y);
;         float y2 = fmix_lo(S[2], r1_, 0.f); y2 = fmix_hi(S[3], r1_, y2);
;         y += y2;
;         if (VAR == 0 && islat) {
;           y = row_sum16(y);
;           if (q == 0) yout[((size_t)dir * NL + row_of(t0 + uu)) * RWW + hh * 64 + vrow] = (h16)y;
;         }
;         if (VAR != 0) asm volatile("" :: "v"(y));
;         const int nstep = t0 + uu + RW_U < RW_NS ? t0 + uu + RW_U : RW_NS - 1;
;         if (VAR != 2) RW_LOAD(uu, nstep);
.Lscan_loop_d0:
	v_mov_b32_dpp v38, v36 row_newbcast:0 row_mask:0xf bank_mask:0xf
	v_fma_mix_f32 v18, v10, v90, 0 op_sel_hi:[0,1,0]
	v_fma_mix_f32 v14, v10, v84, v10 op_sel_hi:[0,1,0]
	v_fma_mix_f32 v18, v11, v90, v18 op_sel:[0,1,0] op_sel_hi:[0,1,0]
	v_fma_mix_f32 v15, v11, v84, v11 op_sel:[0,1,0] op_sel_hi:[0,1,0]
	v_fma_mix_f32 v18, v12, v91, v18 op_sel_hi:[0,1,0]
	v_fma_mix_f32 v16, v12, v85, v12 op_sel_hi:[0,1,0]
	v_fma_mix_f32 v18, v13, v91, v18 op_sel:[0,1,0] op_sel_hi:[0,1,0]
	v_fma_mix_f32 v17, v13, v85, v13 op_sel:[0,1,0] op_sel_hi:[0,1,0]
	v_fma_mix_f32 v14, v38, v86, v14 op_sel_hi:[1,1,0]
	v_fma_mix_f32 v15, v38, v86, v15 op_sel:[0,1,0] op_sel_hi:[1,1,0]
	v_add_f32_dpp v18, v18, v18 quad_perm:[1,0,3,2] row_mask:0xf bank_mask:0xf bound_ctrl:1
	v_fma_mix_f32 v16, v38, v87, v16 op_sel_hi:[1,1,0]
	v_fma_mix_f32 v17, v38, v87, v17 op_sel:[0,1,0] op_sel_hi:[1,1,0]
	v_add_f32_dpp v18, v18, v18 quad_perm:[2,3,0,1] row_mask:0xf bank_mask:0xf bound_ctrl:1
	v_fma_mix_f32 v35, v10, v242, 0 op_sel_hi:[0,1,0]
	v_fma_mix_f32 v35, v11, v242, v35 op_sel:[0,1,0] op_sel_hi:[0,1,0]
	v_add_f32_dpp v18, v18, v18 row_ror:4 row_mask:0xf bank_mask:0xf bound_ctrl:1
	v_fma_mix_f32 v35, v12, v243, v35 op_sel_hi:[0,1,0]
	v_fma_mix_f32 v35, v13, v243, v35 op_sel:[0,1,0] op_sel_hi:[0,1,0]
	v_add_f32_dpp v18, v18, v18 row_ror:8 row_mask:0xf bank_mask:0xf bound_ctrl:1
	s_waitcnt vmcnt(39)
	global_load_dwordx4 v[234:237], v67, s[6:7]
	v_fma_mix_f32 v10, v18, v88, v14 op_sel_hi:[0,1,0]
	global_load_dwordx2 v[238:239], v67, s[6:7] offset:16
	v_fma_mix_f32 v11, v18, v88, v15 op_sel:[0,1,0] op_sel_hi:[0,1,0]
	global_load_dwordx4 v[240:243], v75, s[8:9]
	v_fma_mix_f32 v12, v18, v89, v16 op_sel_hi:[0,1,0]
	v_fma_mix_f32 v13, v18, v89, v17 op_sel:[0,1,0] op_sel_hi:[0,1,0]
	s_cmp_eq_u32 s3, 15
	s_cbranch_scc1 .Lscan_switch_d0
	s_add_u32 s6, s6, 0x18000
	s_addc_u32 s7, s7, 0
	s_add_u32 s8, s8, 0x10000
	s_addc_u32 s9, s9, 0
	s_add_u32 s10, s10, 0x8000
	s_addc_u32 s11, s11, 0
.Lscan_switched_d0:
	global_load_ushort v37, v80, s[10:11]
	s_cmp_lt_u32 s3, 17
	s_cbranch_scc1 .Lscan_noy_d0
	v_add_f32_dpp v20, v20, v20 row_ror:8 row_mask:0xf bank_mask:0xf bound_ctrl:1
	v_add_f32_dpp v21, v21, v21 row_ror:8 row_mask:0xf bank_mask:0xf bound_ctrl:1
	v_add_f32_dpp v22, v22, v22 row_ror:8 row_mask:0xf bank_mask:0xf bound_ctrl:1
	v_add_f32_dpp v23, v23, v23 row_ror:8 row_mask:0xf bank_mask:0xf bound_ctrl:1
	v_add_f32_dpp v24, v24, v24 row_ror:8 row_mask:0xf bank_mask:0xf bound_ctrl:1
	v_add_f32_dpp v25, v25, v25 row_ror:8 row_mask:0xf bank_mask:0xf bound_ctrl:1
	v_add_f32_dpp v26, v26, v26 row_ror:8 row_mask:0xf bank_mask:0xf bound_ctrl:1
	v_add_f32_dpp v27, v27, v27 row_ror:8 row_mask:0xf bank_mask:0xf bound_ctrl:1
	v_add_f32_dpp v20, v28, v28 row_ror:8 row_mask:0xf bank_mask:0xc bound_ctrl:1
	v_add_f32_dpp v21, v29, v29 row_ror:8 row_mask:0xf bank_mask:0xc bound_ctrl:1
	v_add_f32_dpp v22, v30, v30 row_ror:8 row_mask:0xf bank_mask:0xc bound_ctrl:1
	v_add_f32_dpp v23, v31, v31 row_ror:8 row_mask:0xf bank_mask:0xc bound_ctrl:1
	v_add_f32_dpp v24, v32, v32 row_ror:8 row_mask:0xf bank_mask:0xc bound_ctrl:1
	v_add_f32_dpp v25, v33, v33 row_ror:8 row_mask:0xf bank_mask:0xc bound_ctrl:1
	v_add_f32_dpp v26, v34, v34 row_ror:8 row_mask:0xf bank_mask:0xc bound_ctrl:1
	v_add_f32_dpp v27, v35, v35 row_ror:8 row_mask:0xf bank_mask:0xc bound_ctrl:1
	v_add_f32_dpp v20, v20, v20 row_half_mirror row_mask:0xf bank_mask:0xf bound_ctrl:1
	v_add_f32_dpp v21, v21, v21 row_half_mirror row_mask:0xf bank_mask:0xf bound_ctrl:1
	v_add_f32_dpp v22, v22, v22 row_half_mirror row_mask:0xf bank_mask:0xf bound_ctrl:1
	v_add_f32_dpp v23, v23, v23 row_half_mirror row_mask:0xf bank_mask:0xf bound_ctrl:1
	v_add_f32_dpp v20, v24, v24 row_half_mirror row_mask:0xf bank_mask:0xa bound_ctrl:1
	v_add_f32_dpp v21, v25, v25 row_half_mirror row_mask:0xf bank_mask:0xa bound_ctrl:1
	v_add_f32_dpp v22, v26, v26 row_half_mirror row_mask:0xf bank_mask:0xa bound_ctrl:1
	v_add_f32_dpp v23, v27, v27 row_half_mirror row_mask:0xf bank_mask:0xa bound_ctrl:1
	v_add_f32_dpp v20, v20, v20 quad_perm:[1,0,3,2] row_mask:0xf bank_mask:0xf bound_ctrl:1
	v_add_f32_dpp v21, v21, v21 quad_perm:[1,0,3,2] row_mask:0xf bank_mask:0xf bound_ctrl:1
	v_add_f32_dpp v22, v22, v22 quad_perm:[1,0,3,2] row_mask:0xf bank_mask:0xf bound_ctrl:1
	v_add_f32_dpp v23, v23, v23 quad_perm:[1,0,3,2] row_mask:0xf bank_mask:0xf bound_ctrl:1
	v_add_f32_dpp v20, v20, v20 quad_perm:[2,3,0,1] row_mask:0xf bank_mask:0xf bound_ctrl:1
	v_add_f32_dpp v21, v21, v21 quad_perm:[2,3,0,1] row_mask:0xf bank_mask:0xf bound_ctrl:1
	v_add_f32_dpp v22, v22, v22 quad_perm:[2,3,0,1] row_mask:0xf bank_mask:0xf bound_ctrl:1
	v_add_f32_dpp v23, v23, v23 quad_perm:[2,3,0,1] row_mask:0xf bank_mask:0xf bound_ctrl:1
	v_cndmask_b32_e64 v20, v20, v21, s[20:21]
	v_cndmask_b32_e64 v20, v20, v22, s[22:23]
	v_cndmask_b32_e64 v20, v20, v23, s[24:25]
	v_cvt_f16_f32_e32 v81, v20
	global_store_short v80, v81, s[12:13]
	s_add_u32 s12, s12, 0x8000
	s_addc_u32 s13, s13, 0
; __device__ __forceinline__ float row_sum16(float v) { v += __shfl_xor(v, 1); v += __shfl_xor(v, 2); v += __shfl_xor(v, 4); v += __shfl_xor(v, 8); return v; }
; __device__ __forceinline__ float row_sum16(float v) { v += dppf<0xB1>(v); v += dppf<0x4E>(v); v += dppf<0x124>(v); v += dppf<0x128>(v); return v; }
; #define RW_LOAD(slot, step) do { const size_t ro_ = (size_t)row_of(step) * RWW; \
;       s_ok[slot] = *(const h16x8*)((p_rec + ro_ * 3) + urec); s_b[slot] = *(const h16x4*)((p_rec + ro_ * 3) + urec + 8); \
;       s_kr[slot] = *(const h16x8*)((p_sh + ro_ * 2) + ush); s_v[slot] = (p_v + ro_)[uvoff]; } while (0)
; template <int VAR>
; __device__ __forceinline__ void ph_rw_scan(const Params& P) {
;     ...
;         const float vv = (float)s_v[uu];
;         const u32x4 p_ok = __builtin_bit_cast(u32x4, s_ok[uu]), p_kr = __builtin_bit_cast(u32x4, s_kr[uu]);
;         const u32x2 p_bb = __builtin_bit_cast(u32x2, s_b[uu]);
;         const unsigned om0 = p_ok[0], om1 = p_ok[1], kd0 = p_ok[2], kd1 = p_ok[3];
;         const unsigned kk0 = p_kr[0], kk1 = p_kr[1], r0_ = p_kr[2], r1_ = p_kr[3];
;         const unsigned b0_ = p_bb[0], b1_ = p_bb[1];
;         float sa = fmix_lo(S[0], kk0, 0.f); sa = fmix_hi(S[1], kk0, sa);
;         float sb = fmix_lo(S[2], kk1, 0.f); sb = fmix_hi(S[3], kk1, sb);
;         sa = row_sum16(sa + sb);
;         S[0] = fmix_lo(S[0], om0, S[0]); S[1] = fmix_hi(S[1], om0, S[1]); S[2] = fmix_lo(S[2], om1, S[2]); S[3] = fmix_hi(S[3], om1, S[3]);
;         S[0] = fmix_lo(sa, b0_, S[0]); S[1] = fmix_hi(sa, b0_, S[1]); S[2] = fmix_lo(sa, b1_, S[2]); S[3] = fmix_hi(sa, b1_, S[3]);
;         S[0] = fmix_lo(vv, kd0, S[0]); S[1] = fmix_hi(vv, kd0, S[1]); S[2] = fmix_lo(vv, kd1, S[2]); S[3] = fmix_hi(vv, kd1, S[3]);
;         float y = fmix_lo(S[0], r0_, 0.f); y = fmix_hi(S[1], r0_, y);
;         float y2 = fmix_lo(S[2], r1_, 0.f); y2 = fmix_hi(S[3], r1_, y2);
;         y += y2;
;         if (VAR == 0 && islat) {
;           y = row_sum16(y);
;           if (q == 0) yout[((size_t)dir * NL + row_of(t0 + uu)) * RWW + hh * 64 + vrow] = (h16)y;
;         }
;         if (VAR != 0) asm volatile("" :: "v"(y));
;         const int nstep = t0 + uu + RW_U < RW_NS ? t0 + uu + RW_U : RW_NS - 1;
;         if (VAR != 2) RW_LOAD(uu, nstep);
.Lscan_noy_d0:
	v_mov_b32_dpp v38, v36 row_newbcast:1 row_mask:0xf bank_mask:0xf
	v_fma_mix_f32 v18, v10, v100, 0 op_sel_hi:[0,1,0]
	v_fma_mix_f32 v14, v10, v94, v10 op_sel_hi:[0,1,0]
	v_fma_mix_f32 v18, v11, v100, v18 op_sel:[0,1,0] op_sel_hi:[0,1,0]
	v_fma_mix_f32 v15, v11, v94, v11 op_sel:[0,1,0] op_sel_hi:[0,1,0]
	v_fma_mix_f32 v18, v12, v101, v18 op_sel_hi:[0,1,0]
	v_fma_mix_f32 v16, v12, v95, v12 op_sel_hi:[0,1,0]
	v_fma_mix_f32 v18, v13, v101, v18 op_sel:[0,1,0] op_sel_hi:[0,1,0]
	v_fma_mix_f32 v17, v13, v95, v13 op_sel:[0,1,0] op_sel_hi:[0,1,0]
	v_fma_mix_f32 v14, v38, v96, v14 op_sel_hi:[1,1,0]
	v_fma_mix_f32 v15, v38, v96, v15 op_sel:[0,1,0] op_sel_hi:[1,1,0]
	v_add_f32_dpp v18, v18, v18 quad_perm:[1,0,3,2] row_mask:0xf bank_mask:0xf bound_ctrl:1
	v_fma_mix_f32 v16, v38, v97, v16 op_sel_hi:[1,1,0]
	v_fma_mix_f32 v17, v38, v97, v17 op_sel:[0,1,0] op_sel_hi:[1,1,0]
	v_add_f32_dpp v18, v18, v18 quad_perm:[2,3,0,1] row_mask:0xf bank_mask:0xf bound_ctrl:1
	v_fma_mix_f32 v20, v10, v92, 0 op_sel_hi:[0,1,0]
	v_fma_mix_f32 v20, v11, v92, v20 op_sel:[0,1,0] op_sel_hi:[0,1,0]
	v_add_f32_dpp v18, v18, v18 row_ror:4 row_mask:0xf bank_mask:0xf bound_ctrl:1
	v_fma_mix_f32 v20, v12, v93, v20 op_sel_hi:[0,1,0]
	v_fma_mix_f32 v20, v13, v93, v20 op_sel:[0,1,0] op_sel_hi:[0,1,0]
	v_add_f32_dpp v18, v18, v18 row_ror:8 row_mask:0xf bank_mask:0xf bound_ctrl:1
	s_waitcnt vmcnt(39)
	global_load_dwordx4 v[84:87], v52, s[6:7]
	v_fma_mix_f32 v10, v18, v98, v14 op_sel_hi:[0,1,0]
	global_load_dwordx2 v[88:89], v52, s[6:7] offset:16
	v_fma_mix_f32 v11, v18, v98, v15 op_sel:[0,1,0] op_sel_hi:[0,1,0]
	global_load_dwordx4 v[90:93], v68, s[8:9] offset:-4096
	v_fma_mix_f32 v12, v18, v99, v16 op_sel_hi:[0,1,0]
	v_fma_mix_f32 v13, v18, v99, v17 op_sel:[0,1,0] op_sel_hi:[0,1,0]
	v_mov_b32_dpp v38, v36 row_newbcast:2 row_mask:0xf bank_mask:0xf
	v_fma_mix_f32 v18, v10, v110, 0 op_sel_hi:[0,1,0]
	v_fma_mix_f32 v14, v10, v104, v10 op_sel_hi:[0,1,0]
	v_fma_mix_f32 v18, v11, v110, v18 op_sel:[0,1,0] op_sel_hi:[0,1,0]
	v_fma_mix_f32 v15, v11, v104, v11 op_sel:[0,1,0] op_sel_hi:[0,1,0]
	v_fma_mix_f32 v18, v12, v111, v18 op_sel_hi:[0,1,0]
	v_fma_mix_f32 v16, v12, v105, v12 op_sel_hi:[0,1,0]
	v_fma_mix_f32 v18, v13, v111, v18 op_sel:[0,1,0] op_sel_hi:[0,1,0]
	v_fma_mix_f32 v17, v13, v105, v13 op_sel:[0,1,0] op_sel_hi:[0,1,0]
	v_fma_mix_f32 v14, v38, v106, v14 op_sel_hi:[1,1,0]
	v_fma_mix_f32 v15, v38, v106, v15 op_sel:[0,1,0] op_sel_hi:[1,1,0]
	v_add_f32_dpp v18, v18, v18 quad_perm:[1,0,3,2] row_mask:0xf bank_mask:0xf bound_ctrl:1
	v_fma_mix_f32 v16, v38, v107, v16 op_sel_hi:[1,1,0]
	v_fma_mix_f32 v17, v38, v107, v17 op_sel:[0,1,0] op_sel_hi:[1,1,0]
	v_add_f32_dpp v18, v18, v18 quad_perm:[2,3,0,1] row_mask:0xf bank_mask:0xf bound_ctrl:1
	v_fma_mix_f32 v21, v10, v102, 0 op_sel_hi:[0,1,0]
	v_fma_mix_f32 v21, v11, v102, v21 op_sel:[0,1,0] op_sel_hi:[0,1,0]
	v_add_f32_dpp v18, v18, v18 row_ror:4 row_mask:0xf bank_mask:0xf bound_ctrl:1
	v_fma_mix_f32 v21, v12, v103, v21 op_sel_hi:[0,1,0]
	v_fma_mix_f32 v21, v13, v103, v21 op_sel:[0,1,0] op_sel_hi:[0,1,0]
	v_add_f32_dpp v18, v18, v18 row_ror:8 row_mask:0xf bank_mask:0xf bound_ctrl:1
	s_waitcnt vmcnt(39)
	global_load_dwordx4 v[94:97], v53, s[6:7]
	v_fma_mix_f32 v10, v18, v108, v14 op_sel_hi:[0,1,0]
	global_load_dwordx2 v[98:99], v53, s[6:7] offset:16
	v_fma_mix_f32 v11, v18, v108, v15 op_sel:[0,1,0] op_sel_hi:[0,1,0]
	global_load_dwordx4 v[100:103], v68, s[8:9]
	v_fma_mix_f32 v12, v18, v109, v16 op_sel_hi:[0,1,0]
	v_fma_mix_f32 v13, v18, v109, v17 op_sel:[0,1,0] op_sel_hi:[0,1,0]
	v_mov_b32_dpp v38, v36 row_newbcast:3 row_mask:0xf bank_mask:0xf
	v_fma_mix_f32 v18, v10, v120, 0 op_sel_hi:[0,1,0]
	v_fma_mix_f32 v14, v10, v114, v10 op_sel_hi:[0,1,0]
	v_fma_mix_f32 v18, v11, v120, v18 op_sel:[0,1,0] op_sel_hi:[0,1,0]
	v_fma_mix_f32 v15, v11, v114, v11 op_sel:[0,1,0] op_sel_hi:[0,1,0]
	v_fma_mix_f32 v18, v12, v121, v18 op_sel_hi:[0,1,0]
	v_fma_mix_f32 v16, v12, v115, v12 op_sel_hi:[0,1,0]
	v_fma_mix_f32 v18, v13, v121, v18 op_sel:[0,1,0] op_sel_hi:[0,1,0]
	v_fma_mix_f32 v17, v13, v115, v13 op_sel:[0,1,0] op_sel_hi:[0,1,0]
	v_fma_mix_f32 v14, v38, v116, v14 op_sel_hi:[1,1,0]
	v_fma_mix_f32 v15, v38, v116, v15 op_sel:[0,1,0] op_sel_hi:[1,1,0]
	v_add_f32_dpp v18, v18, v18 quad_perm:[1,0,3,2] row_mask:0xf bank_mask:0xf bound_ctrl:1
	v_fma_mix_f32 v16, v38, v117, v16 op_sel_hi:[1,1,0]
	v_fma_mix_f32 v17, v38, v117, v17 op_sel:[0,1,0] op_sel_hi:[1,1,0]
	v_add_f32_dpp v18, v18, v18 quad_perm:[2,3,0,1] row_mask:0xf bank_mask:0xf bound_ctrl:1
	v_fma_mix_f32 v22, v10, v112, 0 op_sel_hi:[0,1,0]
	v_fma_mix_f32 v22, v11, v112, v22 op_sel:[0,1,0] op_sel_hi:[0,1,0]
	v_add_f32_dpp v18, v18, v18 row_ror:4 row_mask:0xf bank_mask:0xf bound_ctrl:1
	v_fma_mix_f32 v22, v12, v113, v22 op_sel_hi:[0,1,0]
	v_fma_mix_f32 v22, v13, v113, v22 op_sel:[0,1,0] op_sel_hi:[0,1,0]
	v_add_f32_dpp v18, v18, v18 row_ror:8 row_mask:0xf bank_mask:0xf bound_ctrl:1
	s_waitcnt vmcnt(39)
; __device__ __forceinline__ float row_sum16(float v) { v += __shfl_xor(v, 1); v += __shfl_xor(v, 2); v += __shfl_xor(v, 4); v += __shfl_xor(v, 8); return v; }
; __device__ __forceinline__ float row_sum16(float v) { v += dppf<0xB1>(v); v += dppf<0x4E>(v); v += dppf<0x124>(v); v += dppf<0x128>(v); return v; }
; #define RW_LOAD(slot, step) do { const size_t ro_ = (size_t)row_of(step) * RWW; \
;       s_ok[slot] = *(const h16x8*)((p_rec + ro_ * 3) + urec); s_b[slot] = *(const h16x4*)((p_rec + ro_ * 3) + urec + 8); \
;       s_kr[slot] = *(const h16x8*)((p_sh + ro_ * 2) + ush); s_v[slot] = (p_v + ro_)[uvoff]; } while (0)
; template <int VAR>
; __device__ __forceinline__ void ph_rw_scan(const Params& P) {
;     ...
;         const float vv = (float)s_v[uu];
;         const u32x4 p_ok = __builtin_bit_cast(u32x4, s_ok[uu]), p_kr = __builtin_bit_cast(u32x4, s_kr[uu]);
;         const u32x2 p_bb = __builtin_bit_cast(u32x2, s_b[uu]);
;         const unsigned om0 = p_ok[0], om1 = p_ok[1], kd0 = p_ok[2], kd1 = p_ok[3];
;         const unsigned kk0 = p_kr[0], kk1 = p_kr[1], r0_ = p_kr[2], r1_ = p_kr[3];
;         const unsigned b0_ = p_bb[0], b1_ = p_bb[1];
;         float sa = fmix_lo(S[0], kk0, 0.f); sa = fmix_hi(S[1], kk0, sa);
;         float sb = fmix_lo(S[2], kk1, 0.f); sb = fmix_hi(S[3], kk1, sb);
;         sa = row_sum16(sa + sb);
;         S[0] = fmix_lo(S[0], om0, S[0]); S[1] = fmix_hi(S[1], om0, S[1]); S[2] = fmix_lo(S[2], om1, S[2]); S[3] = fmix_hi(S[3], om1, S[3]);
;         S[0] = fmix_lo(sa, b0_, S[0]); S[1] = fmix_hi(sa, b0_, S[1]); S[2] = fmix_lo(sa, b1_, S[2]); S[3] = fmix_hi(sa, b1_, S[3]);
;         S[0] = fmix_lo(vv, kd0, S[0]); S[1] = fmix_hi(vv, kd0, S[1]); S[2] = fmix_lo(vv, kd1, S[2]); S[3] = fmix_hi(vv, kd1, S[3]);
;         float y = fmix_lo(S[0], r0_, 0.f); y = fmix_hi(S[1], r0_, y);
;         float y2 = fmix_lo(S[2], r1_, 0.f); y2 = fmix_hi(S[3], r1_, y2);
;         y += y2;
;         if (VAR == 0 && islat) {
;           y = row_sum16(y);
;           if (q == 0) yout[((size_t)dir * NL + row_of(t0 + uu)) * RWW + hh * 64 + vrow] = (h16)y;
;         }
;         if (VAR != 0) asm volatile("" :: "v"(y));
;         const int nstep = t0 + uu + RW_U < RW_NS ? t0 + uu + RW_U : RW_NS - 1;
;         if (VAR != 2) RW_LOAD(uu, nstep);
	global_load_dwordx4 v[104:107], v54, s[6:7]
	v_fma_mix_f32 v10, v18, v118, v14 op_sel_hi:[0,1,0]
	global_load_dwordx2 v[108:109], v54, s[6:7] offset:16
	v_fma_mix_f32 v11, v18, v118, v15 op_sel:[0,1,0] op_sel_hi:[0,1,0]
	global_load_dwordx4 v[110:113], v69, s[8:9] offset:-4096
	v_fma_mix_f32 v12, v18, v119, v16 op_sel_hi:[0,1,0]
	v_fma_mix_f32 v13, v18, v119, v17 op_sel:[0,1,0] op_sel_hi:[0,1,0]
	v_mov_b32_dpp v38, v36 row_newbcast:4 row_mask:0xf bank_mask:0xf
	v_fma_mix_f32 v18, v10, v130, 0 op_sel_hi:[0,1,0]
	v_fma_mix_f32 v14, v10, v124, v10 op_sel_hi:[0,1,0]
	v_fma_mix_f32 v18, v11, v130, v18 op_sel:[0,1,0] op_sel_hi:[0,1,0]
	v_fma_mix_f32 v15, v11, v124, v11 op_sel:[0,1,0] op_sel_hi:[0,1,0]
	v_fma_mix_f32 v18, v12, v131, v18 op_sel_hi:[0,1,0]
	v_fma_mix_f32 v16, v12, v125, v12 op_sel_hi:[0,1,0]
	v_fma_mix_f32 v18, v13, v131, v18 op_sel:[0,1,0] op_sel_hi:[0,1,0]
	v_fma_mix_f32 v17, v13, v125, v13 op_sel:[0,1,0] op_sel_hi:[0,1,0]
	v_fma_mix_f32 v14, v38, v126, v14 op_sel_hi:[1,1,0]
	v_fma_mix_f32 v15, v38, v126, v15 op_sel:[0,1,0] op_sel_hi:[1,1,0]
	v_add_f32_dpp v18, v18, v18 quad_perm:[1,0,3,2] row_mask:0xf bank_mask:0xf bound_ctrl:1
	v_fma_mix_f32 v16, v38, v127, v16 op_sel_hi:[1,1,0]
	v_fma_mix_f32 v17, v38, v127, v17 op_sel:[0,1,0] op_sel_hi:[1,1,0]
	v_add_f32_dpp v18, v18, v18 quad_perm:[2,3,0,1] row_mask:0xf bank_mask:0xf bound_ctrl:1
	v_fma_mix_f32 v23, v10, v122, 0 op_sel_hi:[0,1,0]
	v_fma_mix_f32 v23, v11, v122, v23 op_sel:[0,1,0] op_sel_hi:[0,1,0]
	v_add_f32_dpp v18, v18, v18 row_ror:4 row_mask:0xf bank_mask:0xf bound_ctrl:1
	v_fma_mix_f32 v23, v12, v123, v23 op_sel_hi:[0,1,0]
	v_fma_mix_f32 v23, v13, v123, v23 op_sel:[0,1,0] op_sel_hi:[0,1,0]
	v_add_f32_dpp v18, v18, v18 row_ror:8 row_mask:0xf bank_mask:0xf bound_ctrl:1
	s_waitcnt vmcnt(39)
	global_load_dwordx4 v[114:117], v55, s[6:7]
	v_fma_mix_f32 v10, v18, v128, v14 op_sel_hi:[0,1,0]
	global_load_dwordx2 v[118:119], v55, s[6:7] offset:16
	v_fma_mix_f32 v11, v18, v128, v15 op_sel:[0,1,0] op_sel_hi:[0,1,0]
	global_load_dwordx4 v[120:123], v69, s[8:9]
	v_fma_mix_f32 v12, v18, v129, v16 op_sel_hi:[0,1,0]
	v_fma_mix_f32 v13, v18, v129, v17 op_sel:[0,1,0] op_sel_hi:[0,1,0]
	v_mov_b32_dpp v38, v36 row_newbcast:5 row_mask:0xf bank_mask:0xf
	v_fma_mix_f32 v18, v10, v140, 0 op_sel_hi:[0,1,0]
	v_fma_mix_f32 v14, v10, v134, v10 op_sel_hi:[0,1,0]
	v_fma_mix_f32 v18, v11, v140, v18 op_sel:[0,1,0] op_sel_hi:[0,1,0]
	v_fma_mix_f32 v15, v11, v134, v11 op_sel:[0,1,0] op_sel_hi:[0,1,0]
	v_fma_mix_f32 v18, v12, v141, v18 op_sel_hi:[0,1,0]
	v_fma_mix_f32 v16, v12, v135, v12 op_sel_hi:[0,1,0]
	v_fma_mix_f32 v18, v13, v141, v18 op_sel:[0,1,0] op_sel_hi:[0,1,0]
	v_fma_mix_f32 v17, v13, v135, v13 op_sel:[0,1,0] op_sel_hi:[0,1,0]
	v_fma_mix_f32 v14, v38, v136, v14 op_sel_hi:[1,1,0]
	v_fma_mix_f32 v15, v38, v136, v15 op_sel:[0,1,0] op_sel_hi:[1,1,0]
	v_add_f32_dpp v18, v18, v18 quad_perm:[1,0,3,2] row_mask:0xf bank_mask:0xf bound_ctrl:1
	v_fma_mix_f32 v16, v38, v137, v16 op_sel_hi:[1,1,0]
	v_fma_mix_f32 v17, v38, v137, v17 op_sel:[0,1,0] op_sel_hi:[1,1,0]
	v_add_f32_dpp v18, v18, v18 quad_perm:[2,3,0,1] row_mask:0xf bank_mask:0xf bound_ctrl:1
	v_fma_mix_f32 v24, v10, v132, 0 op_sel_hi:[0,1,0]
	v_fma_mix_f32 v24, v11, v132, v24 op_sel:[0,1,0] op_sel_hi:[0,1,0]
	v_add_f32_dpp v18, v18, v18 row_ror:4 row_mask:0xf bank_mask:0xf bound_ctrl:1
	v_fma_mix_f32 v24, v12, v133, v24 op_sel_hi:[0,1,0]
	v_fma_mix_f32 v24, v13, v133, v24 op_sel:[0,1,0] op_sel_hi:[0,1,0]
	v_add_f32_dpp v18, v18, v18 row_ror:8 row_mask:0xf bank_mask:0xf bound_ctrl:1
	s_waitcnt vmcnt(39)
	global_load_dwordx4 v[124:127], v56, s[6:7]
	v_fma_mix_f32 v10, v18, v138, v14 op_sel_hi:[0,1,0]
	global_load_dwordx2 v[128:129], v56, s[6:7] offset:16
	v_fma_mix_f32 v11, v18, v138, v15 op_sel:[0,1,0] op_sel_hi:[0,1,0]
	global_load_dwordx4 v[130:133], v70, s[8:9] offset:-4096
	v_fma_mix_f32 v12, v18, v139, v16 op_sel_hi:[0,1,0]
	v_fma_mix_f32 v13, v18, v139, v17 op_sel:[0,1,0] op_sel_hi:[0,1,0]
	v_mov_b32_dpp v38, v36 row_newbcast:6 row_mask:0xf bank_mask:0xf
	v_fma_mix_f32 v18, v10, v150, 0 op_sel_hi:[0,1,0]
	v_fma_mix_f32 v14, v10, v144, v10 op_sel_hi:[0,1,0]
	v_fma_mix_f32 v18, v11, v150, v18 op_sel:[0,1,0] op_sel_hi:[0,1,0]
	v_fma_mix_f32 v15, v11, v144, v11 op_sel:[0,1,0] op_sel_hi:[0,1,0]
	v_fma_mix_f32 v18, v12, v151, v18 op_sel_hi:[0,1,0]
	v_fma_mix_f32 v16, v12, v145, v12 op_sel_hi:[0,1,0]
	v_fma_mix_f32 v18, v13, v151, v18 op_sel:[0,1,0] op_sel_hi:[0,1,0]
	v_fma_mix_f32 v17, v13, v145, v13 op_sel:[0,1,0] op_sel_hi:[0,1,0]
	v_fma_mix_f32 v14, v38, v146, v14 op_sel_hi:[1,1,0]
	v_fma_mix_f32 v15, v38, v146, v15 op_sel:[0,1,0] op_sel_hi:[1,1,0]
	v_add_f32_dpp v18, v18, v18 quad_perm:[1,0,3,2] row_mask:0xf bank_mask:0xf bound_ctrl:1
	v_fma_mix_f32 v16, v38, v147, v16 op_sel_hi:[1,1,0]
	v_fma_mix_f32 v17, v38, v147, v17 op_sel:[0,1,0] op_sel_hi:[1,1,0]
	v_add_f32_dpp v18, v18, v18 quad_perm:[2,3,0,1] row_mask:0xf bank_mask:0xf bound_ctrl:1
	v_fma_mix_f32 v25, v10, v142, 0 op_sel_hi:[0,1,0]
	v_fma_mix_f32 v25, v11, v142, v25 op_sel:[0,1,0] op_sel_hi:[0,1,0]
	v_add_f32_dpp v18, v18, v18 row_ror:4 row_mask:0xf bank_mask:0xf bound_ctrl:1
	v_fma_mix_f32 v25, v12, v143, v25 op_sel_hi:[0,1,0]
	v_fma_mix_f32 v25, v13, v143, v25 op_sel:[0,1,0] op_sel_hi:[0,1,0]
	v_add_f32_dpp v18, v18, v18 row_ror:8 row_mask:0xf bank_mask:0xf bound_ctrl:1
	s_waitcnt vmcnt(39)
; __device__ __forceinline__ float row_sum16(float v) { v += __shfl_xor(v, 1); v += __shfl_xor(v, 2); v += __shfl_xor(v, 4); v += __shfl_xor(v, 8); return v; }
; __device__ __forceinline__ float row_sum16(float v) { v += dppf<0xB1>(v); v += dppf<0x4E>(v); v += dppf<0x124>(v); v += dppf<0x128>(v); return v; }
; #define RW_LOAD(slot, step) do { const size_t ro_ = (size_t)row_of(step) * RWW; \
;       s_ok[slot] = *(const h16x8*)((p_rec + ro_ * 3) + urec); s_b[slot] = *(const h16x4*)((p_rec + ro_ * 3) + urec + 8); \
;       s_kr[slot] = *(const h16x8*)((p_sh + ro_ * 2) + ush); s_v[slot] = (p_v + ro_)[uvoff]; } while (0)
; template <int VAR>
; __device__ __forceinline__ void ph_rw_scan(const Params& P) {
;     ...
;         const float vv = (float)s_v[uu];
;         const u32x4 p_ok = __builtin_bit_cast(u32x4, s_ok[uu]), p_kr = __builtin_bit_cast(u32x4, s_kr[uu]);
;         const u32x2 p_bb = __builtin_bit_cast(u32x2, s_b[uu]);
;         const unsigned om0 = p_ok[0], om1 = p_ok[1], kd0 = p_ok[2], kd1 = p_ok[3];
;         const unsigned kk0 = p_kr[0], kk1 = p_kr[1], r0_ = p_kr[2], r1_ = p_kr[3];
;         const unsigned b0_ = p_bb[0], b1_ = p_bb[1];
;         float sa = fmix_lo(S[0], kk0, 0.f); sa = fmix_hi(S[1], kk0, sa);
;         float sb = fmix_lo(S[2], kk1, 0.f); sb = fmix_hi(S[3], kk1, sb);
;         sa = row_sum16(sa + sb);
;         S[0] = fmix_lo(S[0], om0, S[0]); S[1] = fmix_hi(S[1], om0, S[1]); S[2] = fmix_lo(S[2], om1, S[2]); S[3] = fmix_hi(S[3], om1, S[3]);
;         S[0] = fmix_lo(sa, b0_, S[0]); S[1] = fmix_hi(sa, b0_, S[1]); S[2] = fmix_lo(sa, b1_, S[2]); S[3] = fmix_hi(sa, b1_, S[3]);
;         S[0] = fmix_lo(vv, kd0, S[0]); S[1] = fmix_hi(vv, kd0, S[1]); S[2] = fmix_lo(vv, kd1, S[2]); S[3] = fmix_hi(vv, kd1, S[3]);
;         float y = fmix_lo(S[0], r0_, 0.f); y = fmix_hi(S[1], r0_, y);
;         float y2 = fmix_lo(S[2], r1_, 0.f); y2 = fmix_hi(S[3], r1_, y2);
;         y += y2;
;         if (VAR == 0 && islat) {
;           y = row_sum16(y);
;           if (q == 0) yout[((size_t)dir * NL + row_of(t0 + uu)) * RWW + hh * 64 + vrow] = (h16)y;
;         }
;         if (VAR != 0) asm volatile("" :: "v"(y));
;         const int nstep = t0 + uu + RW_U < RW_NS ? t0 + uu + RW_U : RW_NS - 1;
;         if (VAR != 2) RW_LOAD(uu, nstep);
	global_load_dwordx4 v[134:137], v57, s[6:7]
	v_fma_mix_f32 v10, v18, v148, v14 op_sel_hi:[0,1,0]
	global_load_dwordx2 v[138:139], v57, s[6:7] offset:16
	v_fma_mix_f32 v11, v18, v148, v15 op_sel:[0,1,0] op_sel_hi:[0,1,0]
	global_load_dwordx4 v[140:143], v70, s[8:9]
	v_fma_mix_f32 v12, v18, v149, v16 op_sel_hi:[0,1,0]
	v_fma_mix_f32 v13, v18, v149, v17 op_sel:[0,1,0] op_sel_hi:[0,1,0]
	v_mov_b32_dpp v38, v36 row_newbcast:7 row_mask:0xf bank_mask:0xf
	v_fma_mix_f32 v18, v10, v160, 0 op_sel_hi:[0,1,0]
	v_fma_mix_f32 v14, v10, v154, v10 op_sel_hi:[0,1,0]
	v_fma_mix_f32 v18, v11, v160, v18 op_sel:[0,1,0] op_sel_hi:[0,1,0]
	v_fma_mix_f32 v15, v11, v154, v11 op_sel:[0,1,0] op_sel_hi:[0,1,0]
	v_fma_mix_f32 v18, v12, v161, v18 op_sel_hi:[0,1,0]
	v_fma_mix_f32 v16, v12, v155, v12 op_sel_hi:[0,1,0]
	v_fma_mix_f32 v18, v13, v161, v18 op_sel:[0,1,0] op_sel_hi:[0,1,0]
	v_fma_mix_f32 v17, v13, v155, v13 op_sel:[0,1,0] op_sel_hi:[0,1,0]
	v_fma_mix_f32 v14, v38, v156, v14 op_sel_hi:[1,1,0]
	v_fma_mix_f32 v15, v38, v156, v15 op_sel:[0,1,0] op_sel_hi:[1,1,0]
	v_add_f32_dpp v18, v18, v18 quad_perm:[1,0,3,2] row_mask:0xf bank_mask:0xf bound_ctrl:1
	v_fma_mix_f32 v16, v38, v157, v16 op_sel_hi:[1,1,0]
	v_fma_mix_f32 v17, v38, v157, v17 op_sel:[0,1,0] op_sel_hi:[1,1,0]
	v_add_f32_dpp v18, v18, v18 quad_perm:[2,3,0,1] row_mask:0xf bank_mask:0xf bound_ctrl:1
	v_fma_mix_f32 v26, v10, v152, 0 op_sel_hi:[0,1,0]
	v_fma_mix_f32 v26, v11, v152, v26 op_sel:[0,1,0] op_sel_hi:[0,1,0]
	v_add_f32_dpp v18, v18, v18 row_ror:4 row_mask:0xf bank_mask:0xf bound_ctrl:1
	v_fma_mix_f32 v26, v12, v153, v26 op_sel_hi:[0,1,0]
	v_fma_mix_f32 v26, v13, v153, v26 op_sel:[0,1,0] op_sel_hi:[0,1,0]
	v_add_f32_dpp v18, v18, v18 row_ror:8 row_mask:0xf bank_mask:0xf bound_ctrl:1
	s_waitcnt vmcnt(39)
	global_load_dwordx4 v[144:147], v58, s[6:7]
	v_fma_mix_f32 v10, v18, v158, v14 op_sel_hi:[0,1,0]
	global_load_dwordx2 v[148:149], v58, s[6:7] offset:16
	v_fma_mix_f32 v11, v18, v158, v15 op_sel:[0,1,0] op_sel_hi:[0,1,0]
	global_load_dwordx4 v[150:153], v71, s[8:9] offset:-4096
	v_fma_mix_f32 v12, v18, v159, v16 op_sel_hi:[0,1,0]
	v_fma_mix_f32 v13, v18, v159, v17 op_sel:[0,1,0] op_sel_hi:[0,1,0]
	v_mov_b32_dpp v38, v36 row_newbcast:8 row_mask:0xf bank_mask:0xf
	v_fma_mix_f32 v18, v10, v170, 0 op_sel_hi:[0,1,0]
	v_fma_mix_f32 v14, v10, v164, v10 op_sel_hi:[0,1,0]
	v_fma_mix_f32 v18, v11, v170, v18 op_sel:[0,1,0] op_sel_hi:[0,1,0]
	v_fma_mix_f32 v15, v11, v164, v11 op_sel:[0,1,0] op_sel_hi:[0,1,0]
	v_fma_mix_f32 v18, v12, v171, v18 op_sel_hi:[0,1,0]
	v_fma_mix_f32 v16, v12, v165, v12 op_sel_hi:[0,1,0]
	v_fma_mix_f32 v18, v13, v171, v18 op_sel:[0,1,0] op_sel_hi:[0,1,0]
	v_fma_mix_f32 v17, v13, v165, v13 op_sel:[0,1,0] op_sel_hi:[0,1,0]
	v_fma_mix_f32 v14, v38, v166, v14 op_sel_hi:[1,1,0]
	v_fma_mix_f32 v15, v38, v166, v15 op_sel:[0,1,0] op_sel_hi:[1,1,0]
	v_add_f32_dpp v18, v18, v18 quad_perm:[1,0,3,2] row_mask:0xf bank_mask:0xf bound_ctrl:1
	v_fma_mix_f32 v16, v38, v167, v16 op_sel_hi:[1,1,0]
	v_fma_mix_f32 v17, v38, v167, v17 op_sel:[0,1,0] op_sel_hi:[1,1,0]
	v_add_f32_dpp v18, v18, v18 quad_perm:[2,3,0,1] row_mask:0xf bank_mask:0xf bound_ctrl:1
	v_fma_mix_f32 v27, v10, v162, 0 op_sel_hi:[0,1,0]
	v_fma_mix_f32 v27, v11, v162, v27 op_sel:[0,1,0] op_sel_hi:[0,1,0]
	v_add_f32_dpp v18, v18, v18 row_ror:4 row_mask:0xf bank_mask:0xf bound_ctrl:1
	v_fma_mix_f32 v27, v12, v163, v27 op_sel_hi:[0,1,0]
	v_fma_mix_f32 v27, v13, v163, v27 op_sel:[0,1,0] op_sel_hi:[0,1,0]
	v_add_f32_dpp v18, v18, v18 row_ror:8 row_mask:0xf bank_mask:0xf bound_ctrl:1
	s_waitcnt vmcnt(39)
	global_load_dwordx4 v[154:157], v59, s[6:7]
	v_fma_mix_f32 v10, v18, v168, v14 op_sel_hi:[0,1,0]
	global_load_dwordx2 v[158:159], v59, s[6:7] offset:16
	v_fma_mix_f32 v11, v18, v168, v15 op_sel:[0,1,0] op_sel_hi:[0,1,0]
	global_load_dwordx4 v[160:163], v71, s[8:9]
	v_fma_mix_f32 v12, v18, v169, v16 op_sel_hi:[0,1,0]
	v_fma_mix_f32 v13, v18, v169, v17 op_sel:[0,1,0] op_sel_hi:[0,1,0]
	v_mov_b32_dpp v38, v36 row_newbcast:9 row_mask:0xf bank_mask:0xf
	v_fma_mix_f32 v18, v10, v180, 0 op_sel_hi:[0,1,0]
	v_fma_mix_f32 v14, v10, v174, v10 op_sel_hi:[0,1,0]
	v_fma_mix_f32 v18, v11, v180, v18 op_sel:[0,1,0] op_sel_hi:[0,1,0]
	v_fma_mix_f32 v15, v11, v174, v11 op_sel:[0,1,0] op_sel_hi:[0,1,0]
	v_fma_mix_f32 v18, v12, v181, v18 op_sel_hi:[0,1,0]
	v_fma_mix_f32 v16, v12, v175, v12 op_sel_hi:[0,1,0]
	v_fma_mix_f32 v18, v13, v181, v18 op_sel:[0,1,0] op_sel_hi:[0,1,0]
	v_fma_mix_f32 v17, v13, v175, v13 op_sel:[0,1,0] op_sel_hi:[0,1,0]
	v_fma_mix_f32 v14, v38, v176, v14 op_sel_hi:[1,1,0]
	v_fma_mix_f32 v15, v38, v176, v15 op_sel:[0,1,0] op_sel_hi:[1,1,0]
	v_add_f32_dpp v18, v18, v18 quad_perm:[1,0,3,2] row_mask:0xf bank_mask:0xf bound_ctrl:1
	v_fma_mix_f32 v16, v38, v177, v16 op_sel_hi:[1,1,0]
	v_fma_mix_f32 v17, v38, v177, v17 op_sel:[0,1,0] op_sel_hi:[1,1,0]
	v_add_f32_dpp v18, v18, v18 quad_perm:[2,3,0,1] row_mask:0xf bank_mask:0xf bound_ctrl:1
	v_fma_mix_f32 v28, v10, v172, 0 op_sel_hi:[0,1,0]
	v_fma_mix_f32 v28, v11, v172, v28 op_sel:[0,1,0] op_sel_hi:[0,1,0]
	v_add_f32_dpp v18, v18, v18 row_ror:4 row_mask:0xf bank_mask:0xf bound_ctrl:1
	v_fma_mix_f32 v28, v12, v173, v28 op_sel_hi:[0,1,0]
	v_fma_mix_f32 v28, v13, v173, v28 op_sel:[0,1,0] op_sel_hi:[0,1,0]
	v_add_f32_dpp v18, v18, v18 row_ror:8 row_mask:0xf bank_mask:0xf bound_ctrl:1
	s_waitcnt vmcnt(39)
; __device__ __forceinline__ float row_sum16(float v) { v += __shfl_xor(v, 1); v += __shfl_xor(v, 2); v += __shfl_xor(v, 4); v += __shfl_xor(v, 8); return v; }
; __device__ __forceinline__ float row_sum16(float v) { v += dppf<0xB1>(v); v += dppf<0x4E>(v); v += dppf<0x124>(v); v += dppf<0x128>(v); return v; }
; #define RW_LOAD(slot, step) do { const size_t ro_ = (size_t)row_of(step) * RWW; \
;       s_ok[slot] = *(const h16x8*)((p_rec + ro_ * 3) + urec); s_b[slot] = *(const h16x4*)((p_rec + ro_ * 3) + urec + 8); \
;       s_kr[slot] = *(const h16x8*)((p_sh + ro_ * 2) + ush); s_v[slot] = (p_v + ro_)[uvoff]; } while (0)
; template <int VAR>
; __device__ __forceinline__ void ph_rw_scan(const Params& P) {
;     ...
;         const float vv = (float)s_v[uu];
;         const u32x4 p_ok = __builtin_bit_cast(u32x4, s_ok[uu]), p_kr = __builtin_bit_cast(u32x4, s_kr[uu]);
;         const u32x2 p_bb = __builtin_bit_cast(u32x2, s_b[uu]);
;         const unsigned om0 = p_ok[0], om1 = p_ok[1], kd0 = p_ok[2], kd1 = p_ok[3];
;         const unsigned kk0 = p_kr[0], kk1 = p_kr[1], r0_ = p_kr[2], r1_ = p_kr[3];
;         const unsigned b0_ = p_bb[0], b1_ = p_bb[1];
;         float sa = fmix_lo(S[0], kk0, 0.f); sa = fmix_hi(S[1], kk0, sa);
;         float sb = fmix_lo(S[2], kk1, 0.f); sb = fmix_hi(S[3], kk1, sb);
;         sa = row_sum16(sa + sb);
;         S[0] = fmix_lo(S[0], om0, S[0]); S[1] = fmix_hi(S[1], om0, S[1]); S[2] = fmix_lo(S[2], om1, S[2]); S[3] = fmix_hi(S[3], om1, S[3]);
;         S[0] = fmix_lo(sa, b0_, S[0]); S[1] = fmix_hi(sa, b0_, S[1]); S[2] = fmix_lo(sa, b1_, S[2]); S[3] = fmix_hi(sa, b1_, S[3]);
;         S[0] = fmix_lo(vv, kd0, S[0]); S[1] = fmix_hi(vv, kd0, S[1]); S[2] = fmix_lo(vv, kd1, S[2]); S[3] = fmix_hi(vv, kd1, S[3]);
;         float y = fmix_lo(S[0], r0_, 0.f); y = fmix_hi(S[1], r0_, y);
;         float y2 = fmix_lo(S[2], r1_, 0.f); y2 = fmix_hi(S[3], r1_, y2);
;         y += y2;
;         if (VAR == 0 && islat) {
;           y = row_sum16(y);
;           if (q == 0) yout[((size_t)dir * NL + row_of(t0 + uu)) * RWW + hh * 64 + vrow] = (h16)y;
;         }
;         if (VAR != 0) asm volatile("" :: "v"(y));
;         const int nstep = t0 + uu + RW_U < RW_NS ? t0 + uu + RW_U : RW_NS - 1;
;         if (VAR != 2) RW_LOAD(uu, nstep);
	global_load_dwordx4 v[164:167], v60, s[6:7]
	v_fma_mix_f32 v10, v18, v178, v14 op_sel_hi:[0,1,0]
	global_load_dwordx2 v[168:169], v60, s[6:7] offset:16
	v_fma_mix_f32 v11, v18, v178, v15 op_sel:[0,1,0] op_sel_hi:[0,1,0]
	global_load_dwordx4 v[170:173], v72, s[8:9] offset:-4096
	v_fma_mix_f32 v12, v18, v179, v16 op_sel_hi:[0,1,0]
	v_fma_mix_f32 v13, v18, v179, v17 op_sel:[0,1,0] op_sel_hi:[0,1,0]
	v_mov_b32_dpp v38, v36 row_newbcast:10 row_mask:0xf bank_mask:0xf
	v_fma_mix_f32 v18, v10, v190, 0 op_sel_hi:[0,1,0]
	v_fma_mix_f32 v14, v10, v184, v10 op_sel_hi:[0,1,0]
	v_fma_mix_f32 v18, v11, v190, v18 op_sel:[0,1,0] op_sel_hi:[0,1,0]
	v_fma_mix_f32 v15, v11, v184, v11 op_sel:[0,1,0] op_sel_hi:[0,1,0]
	v_fma_mix_f32 v18, v12, v191, v18 op_sel_hi:[0,1,0]
	v_fma_mix_f32 v16, v12, v185, v12 op_sel_hi:[0,1,0]
	v_fma_mix_f32 v18, v13, v191, v18 op_sel:[0,1,0] op_sel_hi:[0,1,0]
	v_fma_mix_f32 v17, v13, v185, v13 op_sel:[0,1,0] op_sel_hi:[0,1,0]
	v_fma_mix_f32 v14, v38, v186, v14 op_sel_hi:[1,1,0]
	v_fma_mix_f32 v15, v38, v186, v15 op_sel:[0,1,0] op_sel_hi:[1,1,0]
	v_add_f32_dpp v18, v18, v18 quad_perm:[1,0,3,2] row_mask:0xf bank_mask:0xf bound_ctrl:1
	v_fma_mix_f32 v16, v38, v187, v16 op_sel_hi:[1,1,0]
	v_fma_mix_f32 v17, v38, v187, v17 op_sel:[0,1,0] op_sel_hi:[1,1,0]
	v_add_f32_dpp v18, v18, v18 quad_perm:[2,3,0,1] row_mask:0xf bank_mask:0xf bound_ctrl:1
	v_fma_mix_f32 v29, v10, v182, 0 op_sel_hi:[0,1,0]
	v_fma_mix_f32 v29, v11, v182, v29 op_sel:[0,1,0] op_sel_hi:[0,1,0]
	v_add_f32_dpp v18, v18, v18 row_ror:4 row_mask:0xf bank_mask:0xf bound_ctrl:1
	v_fma_mix_f32 v29, v12, v183, v29 op_sel_hi:[0,1,0]
	v_fma_mix_f32 v29, v13, v183, v29 op_sel:[0,1,0] op_sel_hi:[0,1,0]
	v_add_f32_dpp v18, v18, v18 row_ror:8 row_mask:0xf bank_mask:0xf bound_ctrl:1
	s_waitcnt vmcnt(39)
	global_load_dwordx4 v[174:177], v61, s[6:7]
	v_fma_mix_f32 v10, v18, v188, v14 op_sel_hi:[0,1,0]
	global_load_dwordx2 v[178:179], v61, s[6:7] offset:16
	v_fma_mix_f32 v11, v18, v188, v15 op_sel:[0,1,0] op_sel_hi:[0,1,0]
	global_load_dwordx4 v[180:183], v72, s[8:9]
	v_fma_mix_f32 v12, v18, v189, v16 op_sel_hi:[0,1,0]
	v_fma_mix_f32 v13, v18, v189, v17 op_sel:[0,1,0] op_sel_hi:[0,1,0]
	v_mov_b32_dpp v38, v36 row_newbcast:11 row_mask:0xf bank_mask:0xf
	v_fma_mix_f32 v18, v10, v200, 0 op_sel_hi:[0,1,0]
	v_fma_mix_f32 v14, v10, v194, v10 op_sel_hi:[0,1,0]
	v_fma_mix_f32 v18, v11, v200, v18 op_sel:[0,1,0] op_sel_hi:[0,1,0]
	v_fma_mix_f32 v15, v11, v194, v11 op_sel:[0,1,0] op_sel_hi:[0,1,0]
	v_fma_mix_f32 v18, v12, v201, v18 op_sel_hi:[0,1,0]
	v_fma_mix_f32 v16, v12, v195, v12 op_sel_hi:[0,1,0]
	v_fma_mix_f32 v18, v13, v201, v18 op_sel:[0,1,0] op_sel_hi:[0,1,0]
	v_fma_mix_f32 v17, v13, v195, v13 op_sel:[0,1,0] op_sel_hi:[0,1,0]
	v_fma_mix_f32 v14, v38, v196, v14 op_sel_hi:[1,1,0]
	v_fma_mix_f32 v15, v38, v196, v15 op_sel:[0,1,0] op_sel_hi:[1,1,0]
	v_add_f32_dpp v18, v18, v18 quad_perm:[1,0,3,2] row_mask:0xf bank_mask:0xf bound_ctrl:1
	v_fma_mix_f32 v16, v38, v197, v16 op_sel_hi:[1,1,0]
	v_fma_mix_f32 v17, v38, v197, v17 op_sel:[0,1,0] op_sel_hi:[1,1,0]
	v_add_f32_dpp v18, v18, v18 quad_perm:[2,3,0,1] row_mask:0xf bank_mask:0xf bound_ctrl:1
	v_fma_mix_f32 v30, v10, v192, 0 op_sel_hi:[0,1,0]
	v_fma_mix_f32 v30, v11, v192, v30 op_sel:[0,1,0] op_sel_hi:[0,1,0]
	v_add_f32_dpp v18, v18, v18 row_ror:4 row_mask:0xf bank_mask:0xf bound_ctrl:1
	v_fma_mix_f32 v30, v12, v193, v30 op_sel_hi:[0,1,0]
	v_fma_mix_f32 v30, v13, v193, v30 op_sel:[0,1,0] op_sel_hi:[0,1,0]
	v_add_f32_dpp v18, v18, v18 row_ror:8 row_mask:0xf bank_mask:0xf bound_ctrl:1
	s_waitcnt vmcnt(39)
	global_load_dwordx4 v[184:187], v62, s[6:7]
	v_fma_mix_f32 v10, v18, v198, v14 op_sel_hi:[0,1,0]
	global_load_dwordx2 v[188:189], v62, s[6:7] offset:16
	v_fma_mix_f32 v11, v18, v198, v15 op_sel:[0,1,0] op_sel_hi:[0,1,0]
	global_load_dwordx4 v[190:193], v73, s[8:9] offset:-4096
	v_fma_mix_f32 v12, v18, v199, v16 op_sel_hi:[0,1,0]
	v_fma_mix_f32 v13, v18, v199, v17 op_sel:[0,1,0] op_sel_hi:[0,1,0]
	v_mov_b32_dpp v38, v36 row_newbcast:12 row_mask:0xf bank_mask:0xf
	v_fma_mix_f32 v18, v10, v210, 0 op_sel_hi:[0,1,0]
	v_fma_mix_f32 v14, v10, v204, v10 op_sel_hi:[0,1,0]
	v_fma_mix_f32 v18, v11, v210, v18 op_sel:[0,1,0] op_sel_hi:[0,1,0]
	v_fma_mix_f32 v15, v11, v204, v11 op_sel:[0,1,0] op_sel_hi:[0,1,0]
	v_fma_mix_f32 v18, v12, v211, v18 op_sel_hi:[0,1,0]
	v_fma_mix_f32 v16, v12, v205, v12 op_sel_hi:[0,1,0]
	v_fma_mix_f32 v18, v13, v211, v18 op_sel:[0,1,0] op_sel_hi:[0,1,0]
	v_fma_mix_f32 v17, v13, v205, v13 op_sel:[0,1,0] op_sel_hi:[0,1,0]
	v_fma_mix_f32 v14, v38, v206, v14 op_sel_hi:[1,1,0]
	v_fma_mix_f32 v15, v38, v206, v15 op_sel:[0,1,0] op_sel_hi:[1,1,0]
	v_add_f32_dpp v18, v18, v18 quad_perm:[1,0,3,2] row_mask:0xf bank_mask:0xf bound_ctrl:1
	v_fma_mix_f32 v16, v38, v207, v16 op_sel_hi:[1,1,0]
	v_fma_mix_f32 v17, v38, v207, v17 op_sel:[0,1,0] op_sel_hi:[1,1,0]
	v_add_f32_dpp v18, v18, v18 quad_perm:[2,3,0,1] row_mask:0xf bank_mask:0xf bound_ctrl:1
	v_fma_mix_f32 v31, v10, v202, 0 op_sel_hi:[0,1,0]
	v_fma_mix_f32 v31, v11, v202, v31 op_sel:[0,1,0] op_sel_hi:[0,1,0]
	v_add_f32_dpp v18, v18, v18 row_ror:4 row_mask:0xf bank_mask:0xf bound_ctrl:1
	v_fma_mix_f32 v31, v12, v203, v31 op_sel_hi:[0,1,0]
	v_fma_mix_f32 v31, v13, v203, v31 op_sel:[0,1,0] op_sel_hi:[0,1,0]
	v_add_f32_dpp v18, v18, v18 row_ror:8 row_mask:0xf bank_mask:0xf bound_ctrl:1
	s_waitcnt vmcnt(39)
; __device__ __forceinline__ float row_sum16(float v) { v += __shfl_xor(v, 1); v += __shfl_xor(v, 2); v += __shfl_xor(v, 4); v += __shfl_xor(v, 8); return v; }
; __device__ __forceinline__ float row_sum16(float v) { v += dppf<0xB1>(v); v += dppf<0x4E>(v); v += dppf<0x124>(v); v += dppf<0x128>(v); return v; }
; #define RW_LOAD(slot, step) do { const size_t ro_ = (size_t)row_of(step) * RWW; \
;       s_ok[slot] = *(const h16x8*)((p_rec + ro_ * 3) + urec); s_b[slot] = *(const h16x4*)((p_rec + ro_ * 3) + urec + 8); \
;       s_kr[slot] = *(const h16x8*)((p_sh + ro_ * 2) + ush); s_v[slot] = (p_v + ro_)[uvoff]; } while (0)
; template <int VAR>
; __device__ __forceinline__ void ph_rw_scan(const Params& P) {
;     ...
;         const float vv = (float)s_v[uu];
;         const u32x4 p_ok = __builtin_bit_cast(u32x4, s_ok[uu]), p_kr = __builtin_bit_cast(u32x4, s_kr[uu]);
;         const u32x2 p_bb = __builtin_bit_cast(u32x2, s_b[uu]);
;         const unsigned om0 = p_ok[0], om1 = p_ok[1], kd0 = p_ok[2], kd1 = p_ok[3];
;         const unsigned kk0 = p_kr[0], kk1 = p_kr[1], r0_ = p_kr[2], r1_ = p_kr[3];
;         const unsigned b0_ = p_bb[0], b1_ = p_bb[1];
;         float sa = fmix_lo(S[0], kk0, 0.f); sa = fmix_hi(S[1], kk0, sa);
;         float sb = fmix_lo(S[2], kk1, 0.f); sb = fmix_hi(S[3], kk1, sb);
;         sa = row_sum16(sa + sb);
;         S[0] = fmix_lo(S[0], om0, S[0]); S[1] = fmix_hi(S[1], om0, S[1]); S[2] = fmix_lo(S[2], om1, S[2]); S[3] = fmix_hi(S[3], om1, S[3]);
;         S[0] = fmix_lo(sa, b0_, S[0]); S[1] = fmix_hi(sa, b0_, S[1]); S[2] = fmix_lo(sa, b1_, S[2]); S[3] = fmix_hi(sa, b1_, S[3]);
;         S[0] = fmix_lo(vv, kd0, S[0]); S[1] = fmix_hi(vv, kd0, S[1]); S[2] = fmix_lo(vv, kd1, S[2]); S[3] = fmix_hi(vv, kd1, S[3]);
;         float y = fmix_lo(S[0], r0_, 0.f); y = fmix_hi(S[1], r0_, y);
;         float y2 = fmix_lo(S[2], r1_, 0.f); y2 = fmix_hi(S[3], r1_, y2);
;         y += y2;
;         if (VAR == 0 && islat) {
;           y = row_sum16(y);
;           if (q == 0) yout[((size_t)dir * NL + row_of(t0 + uu)) * RWW + hh * 64 + vrow] = (h16)y;
;         }
;         if (VAR != 0) asm volatile("" :: "v"(y));
;         const int nstep = t0 + uu + RW_U < RW_NS ? t0 + uu + RW_U : RW_NS - 1;
;         if (VAR != 2) RW_LOAD(uu, nstep);
	global_load_dwordx4 v[194:197], v63, s[6:7]
	v_fma_mix_f32 v10, v18, v208, v14 op_sel_hi:[0,1,0]
	global_load_dwordx2 v[198:199], v63, s[6:7] offset:16
	v_fma_mix_f32 v11, v18, v208, v15 op_sel:[0,1,0] op_sel_hi:[0,1,0]
	global_load_dwordx4 v[200:203], v73, s[8:9]
	v_fma_mix_f32 v12, v18, v209, v16 op_sel_hi:[0,1,0]
	v_fma_mix_f32 v13, v18, v209, v17 op_sel:[0,1,0] op_sel_hi:[0,1,0]
	v_mov_b32_dpp v38, v36 row_newbcast:13 row_mask:0xf bank_mask:0xf
	v_fma_mix_f32 v18, v10, v220, 0 op_sel_hi:[0,1,0]
	v_fma_mix_f32 v14, v10, v214, v10 op_sel_hi:[0,1,0]
	v_fma_mix_f32 v18, v11, v220, v18 op_sel:[0,1,0] op_sel_hi:[0,1,0]
	v_fma_mix_f32 v15, v11, v214, v11 op_sel:[0,1,0] op_sel_hi:[0,1,0]
	v_fma_mix_f32 v18, v12, v221, v18 op_sel_hi:[0,1,0]
	v_fma_mix_f32 v16, v12, v215, v12 op_sel_hi:[0,1,0]
	v_fma_mix_f32 v18, v13, v221, v18 op_sel:[0,1,0] op_sel_hi:[0,1,0]
	v_fma_mix_f32 v17, v13, v215, v13 op_sel:[0,1,0] op_sel_hi:[0,1,0]
	v_fma_mix_f32 v14, v38, v216, v14 op_sel_hi:[1,1,0]
	v_fma_mix_f32 v15, v38, v216, v15 op_sel:[0,1,0] op_sel_hi:[1,1,0]
	v_add_f32_dpp v18, v18, v18 quad_perm:[1,0,3,2] row_mask:0xf bank_mask:0xf bound_ctrl:1
	v_fma_mix_f32 v16, v38, v217, v16 op_sel_hi:[1,1,0]
	v_fma_mix_f32 v17, v38, v217, v17 op_sel:[0,1,0] op_sel_hi:[1,1,0]
	v_add_f32_dpp v18, v18, v18 quad_perm:[2,3,0,1] row_mask:0xf bank_mask:0xf bound_ctrl:1
	v_fma_mix_f32 v32, v10, v212, 0 op_sel_hi:[0,1,0]
	v_fma_mix_f32 v32, v11, v212, v32 op_sel:[0,1,0] op_sel_hi:[0,1,0]
	v_add_f32_dpp v18, v18, v18 row_ror:4 row_mask:0xf bank_mask:0xf bound_ctrl:1
	v_fma_mix_f32 v32, v12, v213, v32 op_sel_hi:[0,1,0]
	v_fma_mix_f32 v32, v13, v213, v32 op_sel:[0,1,0] op_sel_hi:[0,1,0]
	v_add_f32_dpp v18, v18, v18 row_ror:8 row_mask:0xf bank_mask:0xf bound_ctrl:1
	s_waitcnt vmcnt(39)
	global_load_dwordx4 v[204:207], v64, s[6:7]
	v_fma_mix_f32 v10, v18, v218, v14 op_sel_hi:[0,1,0]
	global_load_dwordx2 v[208:209], v64, s[6:7] offset:16
	v_fma_mix_f32 v11, v18, v218, v15 op_sel:[0,1,0] op_sel_hi:[0,1,0]
	global_load_dwordx4 v[210:213], v74, s[8:9] offset:-4096
	v_fma_mix_f32 v12, v18, v219, v16 op_sel_hi:[0,1,0]
	v_fma_mix_f32 v13, v18, v219, v17 op_sel:[0,1,0] op_sel_hi:[0,1,0]
	v_mov_b32_dpp v38, v36 row_newbcast:14 row_mask:0xf bank_mask:0xf
	v_fma_mix_f32 v18, v10, v230, 0 op_sel_hi:[0,1,0]
	v_fma_mix_f32 v14, v10, v224, v10 op_sel_hi:[0,1,0]
	v_fma_mix_f32 v18, v11, v230, v18 op_sel:[0,1,0] op_sel_hi:[0,1,0]
	v_fma_mix_f32 v15, v11, v224, v11 op_sel:[0,1,0] op_sel_hi:[0,1,0]
	v_fma_mix_f32 v18, v12, v231, v18 op_sel_hi:[0,1,0]
	v_fma_mix_f32 v16, v12, v225, v12 op_sel_hi:[0,1,0]
	v_fma_mix_f32 v18, v13, v231, v18 op_sel:[0,1,0] op_sel_hi:[0,1,0]
	v_fma_mix_f32 v17, v13, v225, v13 op_sel:[0,1,0] op_sel_hi:[0,1,0]
	v_fma_mix_f32 v14, v38, v226, v14 op_sel_hi:[1,1,0]
	v_fma_mix_f32 v15, v38, v226, v15 op_sel:[0,1,0] op_sel_hi:[1,1,0]
	v_add_f32_dpp v18, v18, v18 quad_perm:[1,0,3,2] row_mask:0xf bank_mask:0xf bound_ctrl:1
	v_fma_mix_f32 v16, v38, v227, v16 op_sel_hi:[1,1,0]
	v_fma_mix_f32 v17, v38, v227, v17 op_sel:[0,1,0] op_sel_hi:[1,1,0]
	v_add_f32_dpp v18, v18, v18 quad_perm:[2,3,0,1] row_mask:0xf bank_mask:0xf bound_ctrl:1
	v_fma_mix_f32 v33, v10, v222, 0 op_sel_hi:[0,1,0]
	v_fma_mix_f32 v33, v11, v222, v33 op_sel:[0,1,0] op_sel_hi:[0,1,0]
	v_add_f32_dpp v18, v18, v18 row_ror:4 row_mask:0xf bank_mask:0xf bound_ctrl:1
	v_fma_mix_f32 v33, v12, v223, v33 op_sel_hi:[0,1,0]
	v_fma_mix_f32 v33, v13, v223, v33 op_sel:[0,1,0] op_sel_hi:[0,1,0]
	v_add_f32_dpp v18, v18, v18 row_ror:8 row_mask:0xf bank_mask:0xf bound_ctrl:1
	s_waitcnt vmcnt(39)
	global_load_dwordx4 v[214:217], v65, s[6:7]
	v_fma_mix_f32 v10, v18, v228, v14 op_sel_hi:[0,1,0]
	global_load_dwordx2 v[218:219], v65, s[6:7] offset:16
	v_fma_mix_f32 v11, v18, v228, v15 op_sel:[0,1,0] op_sel_hi:[0,1,0]
	global_load_dwordx4 v[220:223], v74, s[8:9]
	v_fma_mix_f32 v12, v18, v229, v16 op_sel_hi:[0,1,0]
	v_fma_mix_f32 v13, v18, v229, v17 op_sel:[0,1,0] op_sel_hi:[0,1,0]
	v_mov_b32_dpp v38, v36 row_newbcast:15 row_mask:0xf bank_mask:0xf
	v_fma_mix_f32 v18, v10, v240, 0 op_sel_hi:[0,1,0]
	v_fma_mix_f32 v14, v10, v234, v10 op_sel_hi:[0,1,0]
	v_fma_mix_f32 v18, v11, v240, v18 op_sel:[0,1,0] op_sel_hi:[0,1,0]
	v_fma_mix_f32 v15, v11, v234, v11 op_sel:[0,1,0] op_sel_hi:[0,1,0]
	v_fma_mix_f32 v18, v12, v241, v18 op_sel_hi:[0,1,0]
	v_fma_mix_f32 v16, v12, v235, v12 op_sel_hi:[0,1,0]
	v_fma_mix_f32 v18, v13, v241, v18 op_sel:[0,1,0] op_sel_hi:[0,1,0]
	v_fma_mix_f32 v17, v13, v235, v13 op_sel:[0,1,0] op_sel_hi:[0,1,0]
	v_fma_mix_f32 v14, v38, v236, v14 op_sel_hi:[1,1,0]
	v_fma_mix_f32 v15, v38, v236, v15 op_sel:[0,1,0] op_sel_hi:[1,1,0]
	v_add_f32_dpp v18, v18, v18 quad_perm:[1,0,3,2] row_mask:0xf bank_mask:0xf bound_ctrl:1
	v_fma_mix_f32 v16, v38, v237, v16 op_sel_hi:[1,1,0]
	v_fma_mix_f32 v17, v38, v237, v17 op_sel:[0,1,0] op_sel_hi:[1,1,0]
	v_add_f32_dpp v18, v18, v18 quad_perm:[2,3,0,1] row_mask:0xf bank_mask:0xf bound_ctrl:1
	v_fma_mix_f32 v34, v10, v232, 0 op_sel_hi:[0,1,0]
	v_fma_mix_f32 v34, v11, v232, v34 op_sel:[0,1,0] op_sel_hi:[0,1,0]
	v_add_f32_dpp v18, v18, v18 row_ror:4 row_mask:0xf bank_mask:0xf bound_ctrl:1
	v_fma_mix_f32 v34, v12, v233, v34 op_sel_hi:[0,1,0]
	v_fma_mix_f32 v34, v13, v233, v34 op_sel:[0,1,0] op_sel_hi:[0,1,0]
	v_add_f32_dpp v18, v18, v18 row_ror:8 row_mask:0xf bank_mask:0xf bound_ctrl:1
	s_waitcnt vmcnt(39)
	global_load_dwordx4 v[224:227], v66, s[6:7]
	v_fma_mix_f32 v10, v18, v238, v14 op_sel_hi:[0,1,0]
	global_load_dwordx2 v[228:229], v66, s[6:7] offset:16
	v_fma_mix_f32 v11, v18, v238, v15 op_sel:[0,1,0] op_sel_hi:[0,1,0]
	global_load_dwordx4 v[230:233], v75, s[8:9] offset:-4096
	v_fma_mix_f32 v12, v18, v239, v16 op_sel_hi:[0,1,0]
	v_fma_mix_f32 v13, v18, v239, v17 op_sel:[0,1,0] op_sel_hi:[0,1,0]
	v_mov_b32_e32 v36, v37
	s_add_u32 s3, s3, 1
	s_cmp_lt_u32 s3, 0x410
	s_cbranch_scc1 .Lscan_loop_d0
; __device__ __forceinline__ float row_sum16(float v) { v += __shfl_xor(v, 1); v += __shfl_xor(v, 2); v += __shfl_xor(v, 4); v += __shfl_xor(v, 8); return v; }
; __device__ __forceinline__ float row_sum16(float v) { v += dppf<0xB1>(v); v += dppf<0x4E>(v); v += dppf<0x124>(v); v += dppf<0x128>(v); return v; }
; template <int VAR>
; __device__ __forceinline__ void ph_rw_scan(const Params& P) {
;     ...
;         float y = fmix_lo(S[0], r0_, 0.f); y = fmix_hi(S[1], r0_, y);
;         float y2 = fmix_lo(S[2], r1_, 0.f); y2 = fmix_hi(S[3], r1_, y2);
;         y += y2;
;         if (VAR == 0 && islat) {
;           y = row_sum16(y);
;           if (q == 0) yout[((size_t)dir * NL + row_of(t0 + uu)) * RWW + hh * 64 + vrow] = (h16)y;
;         }
	v_fma_mix_f32 v35, v10, v242, 0 op_sel_hi:[0,1,0]
	v_fma_mix_f32 v35, v11, v242, v35 op_sel:[0,1,0] op_sel_hi:[0,1,0]
	v_fma_mix_f32 v35, v12, v243, v35 op_sel_hi:[0,1,0]
	v_fma_mix_f32 v35, v13, v243, v35 op_sel:[0,1,0] op_sel_hi:[0,1,0]
	s_nop 1
	v_add_f32_dpp v20, v20, v20 row_ror:8 row_mask:0xf bank_mask:0xf bound_ctrl:1
	v_add_f32_dpp v21, v21, v21 row_ror:8 row_mask:0xf bank_mask:0xf bound_ctrl:1
	v_add_f32_dpp v22, v22, v22 row_ror:8 row_mask:0xf bank_mask:0xf bound_ctrl:1
	v_add_f32_dpp v23, v23, v23 row_ror:8 row_mask:0xf bank_mask:0xf bound_ctrl:1
	v_add_f32_dpp v24, v24, v24 row_ror:8 row_mask:0xf bank_mask:0xf bound_ctrl:1
	v_add_f32_dpp v25, v25, v25 row_ror:8 row_mask:0xf bank_mask:0xf bound_ctrl:1
	v_add_f32_dpp v26, v26, v26 row_ror:8 row_mask:0xf bank_mask:0xf bound_ctrl:1
	v_add_f32_dpp v27, v27, v27 row_ror:8 row_mask:0xf bank_mask:0xf bound_ctrl:1
	v_add_f32_dpp v20, v28, v28 row_ror:8 row_mask:0xf bank_mask:0xc bound_ctrl:1
	v_add_f32_dpp v21, v29, v29 row_ror:8 row_mask:0xf bank_mask:0xc bound_ctrl:1
	v_add_f32_dpp v22, v30, v30 row_ror:8 row_mask:0xf bank_mask:0xc bound_ctrl:1
	v_add_f32_dpp v23, v31, v31 row_ror:8 row_mask:0xf bank_mask:0xc bound_ctrl:1
	v_add_f32_dpp v24, v32, v32 row_ror:8 row_mask:0xf bank_mask:0xc bound_ctrl:1
	v_add_f32_dpp v25, v33, v33 row_ror:8 row_mask:0xf bank_mask:0xc bound_ctrl:1
	v_add_f32_dpp v26, v34, v34 row_ror:8 row_mask:0xf bank_mask:0xc bound_ctrl:1
	v_add_f32_dpp v27, v35, v35 row_ror:8 row_mask:0xf bank_mask:0xc bound_ctrl:1
	v_add_f32_dpp v20, v20, v20 row_half_mirror row_mask:0xf bank_mask:0xf bound_ctrl:1
	v_add_f32_dpp v21, v21, v21 row_half_mirror row_mask:0xf bank_mask:0xf bound_ctrl:1
	v_add_f32_dpp v22, v22, v22 row_half_mirror row_mask:0xf bank_mask:0xf bound_ctrl:1
	v_add_f32_dpp v23, v23, v23 row_half_mirror row_mask:0xf bank_mask:0xf bound_ctrl:1
	v_add_f32_dpp v20, v24, v24 row_half_mirror row_mask:0xf bank_mask:0xa bound_ctrl:1
	v_add_f32_dpp v21, v25, v25 row_half_mirror row_mask:0xf bank_mask:0xa bound_ctrl:1
	v_add_f32_dpp v22, v26, v26 row_half_mirror row_mask:0xf bank_mask:0xa bound_ctrl:1
	v_add_f32_dpp v23, v27, v27 row_half_mirror row_mask:0xf bank_mask:0xa bound_ctrl:1
	v_add_f32_dpp v20, v20, v20 quad_perm:[1,0,3,2] row_mask:0xf bank_mask:0xf bound_ctrl:1
	v_add_f32_dpp v21, v21, v21 quad_perm:[1,0,3,2] row_mask:0xf bank_mask:0xf bound_ctrl:1
	v_add_f32_dpp v22, v22, v22 quad_perm:[1,0,3,2] row_mask:0xf bank_mask:0xf bound_ctrl:1
	v_add_f32_dpp v23, v23, v23 quad_perm:[1,0,3,2] row_mask:0xf bank_mask:0xf bound_ctrl:1
	v_add_f32_dpp v20, v20, v20 quad_perm:[2,3,0,1] row_mask:0xf bank_mask:0xf bound_ctrl:1
	v_add_f32_dpp v21, v21, v21 quad_perm:[2,3,0,1] row_mask:0xf bank_mask:0xf bound_ctrl:1
	v_add_f32_dpp v22, v22, v22 quad_perm:[2,3,0,1] row_mask:0xf bank_mask:0xf bound_ctrl:1
	v_add_f32_dpp v23, v23, v23 quad_perm:[2,3,0,1] row_mask:0xf bank_mask:0xf bound_ctrl:1
	v_cndmask_b32_e64 v20, v20, v21, s[20:21]
	v_cndmask_b32_e64 v20, v20, v22, s[22:23]
	v_cndmask_b32_e64 v20, v20, v23, s[24:25]
	v_cvt_f16_f32_e32 v81, v20
	global_store_short v80, v81, s[12:13]
	s_add_u32 s12, s12, 0x8000
	s_addc_u32 s13, s13, 0
	s_waitcnt vmcnt(0)
	s_branch .Lscan_next

; __device__ __forceinline__ float row_sum16(float v) { v += __shfl_xor(v, 1); v += __shfl_xor(v, 2); v += __shfl_xor(v, 4); v += __shfl_xor(v, 8); return v; }
; __device__ __forceinline__ float row_sum16(float v) { v += dppf<0xB1>(v); v += dppf<0x4E>(v); v += dppf<0x124>(v); v += dppf<0x128>(v); return v; }
; template <int VAR>
; __device__ __forceinline__ void ph_rw_scan(const Params& P) {
;     ...
;     const int rg = wu % 16, hh = (wu / 16) % RW_H, b = (wu / (16 * RW_H)) % BATCH, dir = wu / (16 * RW_H * BATCH);
;     const int vrow = rg * 4 + rl;
;     ...
;     const unsigned g_ = (unsigned)(hh * 16 + q);
;     const unsigned uvoff = (unsigned)(hh * 64 + vrow), urec = g_ * 12u, ush = g_ * 8u;
;     h16x8 s_ok[RW_U], s_kr[RW_U]; h16x4 s_b[RW_U]; h16 s_v[RW_U];
;     auto row_of = [&](int step) -> int {
;       if (step < CTX_LEN) return NL + b * CTX_LEN + (dir == 0 ? step : CTX_LEN - 1 - step);
;       const int s = step - CTX_LEN; return b * SEQ + (dir == 0 ? s : SEQ - 1 - s);
;     };
;     ...
; #pragma unroll
;     for (int uu = 0; uu < RW_U; ++uu) RW_LOAD(uu, uu);
;     ...
;       for (int uu = 0; uu < RW_U; ++uu) {
;         const float vv = (float)s_v[uu];
;         const u32x4 p_ok = __builtin_bit_cast(u32x4, s_ok[uu]), p_kr = __builtin_bit_cast(u32x4, s_kr[uu]);
;         const u32x2 p_bb = __builtin_bit_cast(u32x2, s_b[uu]);
;         const unsigned om0 = p_ok[0], om1 = p_ok[1], kd0 = p_ok[2], kd1 = p_ok[3];
;         const unsigned kk0 = p_kr[0], kk1 = p_kr[1], r0_ = p_kr[2], r1_ = p_kr[3];
;         const unsigned b0_ = p_bb[0], b1_ = p_bb[1];
;         float sa = fmix_lo(S[0], kk0, 0.f); sa = fmix_hi(S[1], kk0, sa);
;         float sb = fmix_lo(S[2], kk1, 0.f); sb = fmix_hi(S[3], kk1, sb);
;         sa = row_sum16(sa + sb);
;         S[0] = fmix_lo(S[0], om0, S[0]); S[1] = fmix_hi(S[1], om0, S[1]); S[2] = fmix_lo(S[2], om1, S[2]); S[3] = fmix_hi(S[3], om1, S[3]);
;         S[0] = fmix_lo(sa, b0_, S[0]); S[1] = fmix_hi(sa, b0_, S[1]); S[2] = fmix_lo(sa, b1_, S[2]); S[3] = fmix_hi(sa, b1_, S[3]);
;         S[0] = fmix_lo(vv, kd0, S[0]); S[1] = fmix_hi(vv, kd0, S[1]); S[2] = fmix_lo(vv, kd1, S[2]); S[3] = fmix_hi(vv, kd1, S[3]);
;         float y = fmix_lo(S[0], r0_, 0.f); y = fmix_hi(S[1], r0_, y);
;         float y2 = fmix_lo(S[2], r1_, 0.f); y2 = fmix_hi(S[3], r1_, y2);
;         y += y2;
.Lscan_dir1:
	v_add_u32_e32 v52, 0x16800, v5
	v_add_u32_e32 v53, 0x15000, v5
	v_add_u32_e32 v54, 0x13800, v5
	v_add_u32_e32 v55, 0x12000, v5
	v_add_u32_e32 v56, 0x10800, v5
	v_add_u32_e32 v57, 0xf000, v5
	v_add_u32_e32 v58, 0xd800, v5
	v_add_u32_e32 v59, 0xc000, v5
	v_add_u32_e32 v60, 0xa800, v5
	v_add_u32_e32 v61, 0x9000, v5
	v_add_u32_e32 v62, 0x7800, v5
	v_add_u32_e32 v63, 0x6000, v5
	v_add_u32_e32 v64, 0x4800, v5
	v_add_u32_e32 v65, 0x3000, v5
	v_add_u32_e32 v66, 0x1800, v5
	v_mov_b32_e32 v67, v5
	v_add_u32_e32 v68, 0xf000, v6
	v_add_u32_e32 v69, 0xd000, v6
	v_add_u32_e32 v70, 0xb000, v6
	v_add_u32_e32 v71, 0x9000, v6
	v_add_u32_e32 v72, 0x7000, v6
	v_add_u32_e32 v73, 0x5000, v6
	v_add_u32_e32 v74, 0x3000, v6
	v_add_u32_e32 v75, 0x1000, v6
	v_add_u32_e32 v76, 0x7000, v7
	v_add_u32_e32 v77, 0x5000, v7
	v_add_u32_e32 v78, 0x3000, v7
	v_add_u32_e32 v79, 0x1000, v7
	v_sub_u32_e32 v81, 15, v2
	v_lshlrev_b32_e32 v80, 11, v81
	v_add_u32_e32 v80, v80, v7
	s_lshl_b32 s30, s28, 8
	s_add_u32 s30, s30, 0x80f0
	s_lshl_b32 s31, s28, 14
	s_add_u32 s31, s31, 0x3ff0
	s_mul_i32 s1, s30, 0x1800
	s_add_u32 s6, s4, s1
	s_addc_u32 s7, s5, 0
	s_add_u32 s6, s6, 0x2f914000
	s_addc_u32 s7, s7, 0
	s_mul_i32 s1, s30, 0x1000
	s_add_u32 s8, s4, s1
	s_addc_u32 s9, s5, 0
	s_add_u32 s8, s8, 0xbe4c000
	s_addc_u32 s9, s9, 0
	s_mul_i32 s1, s30, 0x800
	s_add_u32 s10, s4, s1
	s_addc_u32 s11, s5, 0
	s_add_u32 s10, s10, 0x3bc14000
	s_addc_u32 s11, s11, 0
	s_mul_i32 s1, s31, 0x1800
	s_add_u32 s14, s4, s1
	s_addc_u32 s15, s5, 0
	s_add_u32 s14, s14, 0x2f914000
	s_addc_u32 s15, s15, 0
	s_mul_i32 s1, s31, 0x1000
	s_add_u32 s16, s4, s1
	s_addc_u32 s17, s5, 0
	s_add_u32 s16, s16, 0xbe4c000
	s_addc_u32 s17, s17, 0
	s_mul_i32 s1, s31, 0x800
	s_add_u32 s18, s4, s1
	s_addc_u32 s19, s5, 0
	s_add_u32 s18, s18, 0x3bc14000
	s_addc_u32 s19, s19, 0
	s_mul_i32 s1, s31, 0x800
	s_add_u32 s12, s4, s1
	s_addc_u32 s13, s5, 0
	s_add_u32 s12, s12, 0x1a0cc000
	s_addc_u32 s13, s13, 0
	v_mov_b32_e32 v10, 0
	v_mov_b32_e32 v11, 0
	v_mov_b32_e32 v12, 0
	v_mov_b32_e32 v13, 0
	global_load_ushort v36, v80, s[10:11]
	global_load_dwordx4 v[84:87], v52, s[6:7]
	global_load_dwordx2 v[88:89], v52, s[6:7] offset:16
	global_load_dwordx4 v[90:93], v68, s[8:9]
	global_load_dwordx4 v[94:97], v53, s[6:7]
	global_load_dwordx2 v[98:99], v53, s[6:7] offset:16
	global_load_dwordx4 v[100:103], v68, s[8:9] offset:-4096
	global_load_dwordx4 v[104:107], v54, s[6:7]
	global_load_dwordx2 v[108:109], v54, s[6:7] offset:16
	global_load_dwordx4 v[110:113], v69, s[8:9]
	global_load_dwordx4 v[114:117], v55, s[6:7]
	global_load_dwordx2 v[118:119], v55, s[6:7] offset:16
	global_load_dwordx4 v[120:123], v69, s[8:9] offset:-4096
	global_load_dwordx4 v[124:127], v56, s[6:7]
	global_load_dwordx2 v[128:129], v56, s[6:7] offset:16
	global_load_dwordx4 v[130:133], v70, s[8:9]
	global_load_dwordx4 v[134:137], v57, s[6:7]
	global_load_dwordx2 v[138:139], v57, s[6:7] offset:16
	global_load_dwordx4 v[140:143], v70, s[8:9] offset:-4096
	global_load_dwordx4 v[144:147], v58, s[6:7]
	global_load_dwordx2 v[148:149], v58, s[6:7] offset:16
	global_load_dwordx4 v[150:153], v71, s[8:9]
	global_load_dwordx4 v[154:157], v59, s[6:7]
	global_load_dwordx2 v[158:159], v59, s[6:7] offset:16
	global_load_dwordx4 v[160:163], v71, s[8:9] offset:-4096
	global_load_dwordx4 v[164:167], v60, s[6:7]
	global_load_dwordx2 v[168:169], v60, s[6:7] offset:16
	global_load_dwordx4 v[170:173], v72, s[8:9]
	global_load_dwordx4 v[174:177], v61, s[6:7]
	global_load_dwordx2 v[178:179], v61, s[6:7] offset:16
	global_load_dwordx4 v[180:183], v72, s[8:9] offset:-4096
	global_load_dwordx4 v[184:187], v62, s[6:7]
	global_load_dwordx2 v[188:189], v62, s[6:7] offset:16
	global_load_dwordx4 v[190:193], v73, s[8:9]
	global_load_dwordx4 v[194:197], v63, s[6:7]
	global_load_dwordx2 v[198:199], v63, s[6:7] offset:16
	global_load_dwordx4 v[200:203], v73, s[8:9] offset:-4096
	global_load_dwordx4 v[204:207], v64, s[6:7]
	global_load_dwordx2 v[208:209], v64, s[6:7] offset:16
	global_load_dwordx4 v[210:213], v74, s[8:9]
	global_load_dwordx4 v[214:217], v65, s[6:7]
	global_load_dwordx2 v[218:219], v65, s[6:7] offset:16
	global_load_dwordx4 v[220:223], v74, s[8:9] offset:-4096
	global_load_dwordx4 v[224:227], v66, s[6:7]
	global_load_dwordx2 v[228:229], v66, s[6:7] offset:16
	global_load_dwordx4 v[230:233], v75, s[8:9]
	s_mov_b32 s3, 0
	s_waitcnt vmcnt(42)
.Lscan_loop_d1:
	v_mov_b32_dpp v38, v36 row_newbcast:0 row_mask:0xf bank_mask:0xf
	v_fma_mix_f32 v18, v10, v90, 0 op_sel_hi:[0,1,0]
	v_fma_mix_f32 v14, v10, v84, v10 op_sel_hi:[0,1,0]
	v_fma_mix_f32 v18, v11, v90, v18 op_sel:[0,1,0] op_sel_hi:[0,1,0]
	v_fma_mix_f32 v15, v11, v84, v11 op_sel:[0,1,0] op_sel_hi:[0,1,0]
	v_fma_mix_f32 v18, v12, v91, v18 op_sel_hi:[0,1,0]
	v_fma_mix_f32 v16, v12, v85, v12 op_sel_hi:[0,1,0]
	v_fma_mix_f32 v18, v13, v91, v18 op_sel:[0,1,0] op_sel_hi:[0,1,0]
	v_fma_mix_f32 v17, v13, v85, v13 op_sel:[0,1,0] op_sel_hi:[0,1,0]
	v_fma_mix_f32 v14, v38, v86, v14 op_sel_hi:[1,1,0]
	v_fma_mix_f32 v15, v38, v86, v15 op_sel:[0,1,0] op_sel_hi:[1,1,0]
	v_add_f32_dpp v18, v18, v18 quad_perm:[1,0,3,2] row_mask:0xf bank_mask:0xf bound_ctrl:1
	v_fma_mix_f32 v16, v38, v87, v16 op_sel_hi:[1,1,0]
	v_fma_mix_f32 v17, v38, v87, v17 op_sel:[0,1,0] op_sel_hi:[1,1,0]
	v_add_f32_dpp v18, v18, v18 quad_perm:[2,3,0,1] row_mask:0xf bank_mask:0xf bound_ctrl:1
	v_fma_mix_f32 v35, v10, v242, 0 op_sel_hi:[0,1,0]
	v_fma_mix_f32 v35, v11, v242, v35 op_sel:[0,1,0] op_sel_hi:[0,1,0]
	v_add_f32_dpp v18, v18, v18 row_ror:4 row_mask:0xf bank_mask:0xf bound_ctrl:1
	v_fma_mix_f32 v35, v12, v243, v35 op_sel_hi:[0,1,0]
	v_fma_mix_f32 v35, v13, v243, v35 op_sel:[0,1,0] op_sel_hi:[0,1,0]
	v_add_f32_dpp v18, v18, v18 row_ror:8 row_mask:0xf bank_mask:0xf bound_ctrl:1
	s_waitcnt vmcnt(39)
	global_load_dwordx4 v[234:237], v67, s[6:7]
	v_fma_mix_f32 v10, v18, v88, v14 op_sel_hi:[0,1,0]
	global_load_dwordx2 v[238:239], v67, s[6:7] offset:16
	v_fma_mix_f32 v11, v18, v88, v15 op_sel:[0,1,0] op_sel_hi:[0,1,0]
	global_load_dwordx4 v[240:243], v75, s[8:9] offset:-4096
	v_fma_mix_f32 v12, v18, v89, v16 op_sel_hi:[0,1,0]
	v_fma_mix_f32 v13, v18, v89, v17 op_sel:[0,1,0] op_sel_hi:[0,1,0]
	s_cmp_eq_u32 s3, 15
	s_cbranch_scc1 .Lscan_switch_d1
	s_sub_u32 s6, s6, 0x18000
	s_subb_u32 s7, s7, 0
	s_sub_u32 s8, s8, 0x10000
	s_subb_u32 s9, s9, 0
	s_sub_u32 s10, s10, 0x8000
	s_subb_u32 s11, s11, 0
; __device__ __forceinline__ float row_sum16(float v) { v += __shfl_xor(v, 1); v += __shfl_xor(v, 2); v += __shfl_xor(v, 4); v += __shfl_xor(v, 8); return v; }
; __device__ __forceinline__ float row_sum16(float v) { v += dppf<0xB1>(v); v += dppf<0x4E>(v); v += dppf<0x124>(v); v += dppf<0x128>(v); return v; }
; #define RW_LOAD(slot, step) do { const size_t ro_ = (size_t)row_of(step) * RWW; \
;       s_ok[slot] = *(const h16x8*)((p_rec + ro_ * 3) + urec); s_b[slot] = *(const h16x4*)((p_rec + ro_ * 3) + urec + 8); \
;       s_kr[slot] = *(const h16x8*)((p_sh + ro_ * 2) + ush); s_v[slot] = (p_v + ro_)[uvoff]; } while (0)
; template <int VAR>
; __device__ __forceinline__ void ph_rw_scan(const Params& P) {
;     ...
;       for (int uu = 0; uu < RW_U; ++uu) {
;         const float vv = (float)s_v[uu];
;         const u32x4 p_ok = __builtin_bit_cast(u32x4, s_ok[uu]), p_kr = __builtin_bit_cast(u32x4, s_kr[uu]);
;         const u32x2 p_bb = __builtin_bit_cast(u32x2, s_b[uu]);
;         const unsigned om0 = p_ok[0], om1 = p_ok[1], kd0 = p_ok[2], kd1 = p_ok[3];
;         const unsigned kk0 = p_kr[0], kk1 = p_kr[1], r0_ = p_kr[2], r1_ = p_kr[3];
;         const unsigned b0_ = p_bb[0], b1_ = p_bb[1];
;         float sa = fmix_lo(S[0], kk0, 0.f); sa = fmix_hi(S[1], kk0, sa);
;         float sb = fmix_lo(S[2], kk1, 0.f); sb = fmix_hi(S[3], kk1, sb);
;         sa = row_sum16(sa + sb);
;         S[0] = fmix_lo(S[0], om0, S[0]); S[1] = fmix_hi(S[1], om0, S[1]); S[2] = fmix_lo(S[2], om1, S[2]); S[3] = fmix_hi(S[3], om1, S[3]);
;         S[0] = fmix_lo(sa, b0_, S[0]); S[1] = fmix_hi(sa, b0_, S[1]); S[2] = fmix_lo(sa, b1_, S[2]); S[3] = fmix_hi(sa, b1_, S[3]);
;         S[0] = fmix_lo(vv, kd0, S[0]); S[1] = fmix_hi(vv, kd0, S[1]); S[2] = fmix_lo(vv, kd1, S[2]); S[3] = fmix_hi(vv, kd1, S[3]);
;         float y = fmix_lo(S[0], r0_, 0.f); y = fmix_hi(S[1], r0_, y);
;         float y2 = fmix_lo(S[2], r1_, 0.f); y2 = fmix_hi(S[3], r1_, y2);
;         y += y2;
;         if (VAR == 0 && islat) {
;           y = row_sum16(y);
;           if (q == 0) yout[((size_t)dir * NL + row_of(t0 + uu)) * RWW + hh * 64 + vrow] = (h16)y;
;         }
;         if (VAR != 0) asm volatile("" :: "v"(y));
;         const int nstep = t0 + uu + RW_U < RW_NS ? t0 + uu + RW_U : RW_NS - 1;
;         if (VAR != 2) RW_LOAD(uu, nstep);
.Lscan_switched_d1:
	global_load_ushort v37, v80, s[10:11]
	s_cmp_lt_u32 s3, 17
	s_cbranch_scc1 .Lscan_noy_d1
	v_add_f32_dpp v20, v20, v20 row_ror:8 row_mask:0xf bank_mask:0xf bound_ctrl:1
	v_add_f32_dpp v21, v21, v21 row_ror:8 row_mask:0xf bank_mask:0xf bound_ctrl:1
	v_add_f32_dpp v22, v22, v22 row_ror:8 row_mask:0xf bank_mask:0xf bound_ctrl:1
	v_add_f32_dpp v23, v23, v23 row_ror:8 row_mask:0xf bank_mask:0xf bound_ctrl:1
	v_add_f32_dpp v24, v24, v24 row_ror:8 row_mask:0xf bank_mask:0xf bound_ctrl:1
	v_add_f32_dpp v25, v25, v25 row_ror:8 row_mask:0xf bank_mask:0xf bound_ctrl:1
	v_add_f32_dpp v26, v26, v26 row_ror:8 row_mask:0xf bank_mask:0xf bound_ctrl:1
	v_add_f32_dpp v27, v27, v27 row_ror:8 row_mask:0xf bank_mask:0xf bound_ctrl:1
	v_add_f32_dpp v20, v28, v28 row_ror:8 row_mask:0xf bank_mask:0xc bound_ctrl:1
	v_add_f32_dpp v21, v29, v29 row_ror:8 row_mask:0xf bank_mask:0xc bound_ctrl:1
	v_add_f32_dpp v22, v30, v30 row_ror:8 row_mask:0xf bank_mask:0xc bound_ctrl:1
	v_add_f32_dpp v23, v31, v31 row_ror:8 row_mask:0xf bank_mask:0xc bound_ctrl:1
	v_add_f32_dpp v24, v32, v32 row_ror:8 row_mask:0xf bank_mask:0xc bound_ctrl:1
	v_add_f32_dpp v25, v33, v33 row_ror:8 row_mask:0xf bank_mask:0xc bound_ctrl:1
	v_add_f32_dpp v26, v34, v34 row_ror:8 row_mask:0xf bank_mask:0xc bound_ctrl:1
	v_add_f32_dpp v27, v35, v35 row_ror:8 row_mask:0xf bank_mask:0xc bound_ctrl:1
	v_add_f32_dpp v20, v20, v20 row_half_mirror row_mask:0xf bank_mask:0xf bound_ctrl:1
	v_add_f32_dpp v21, v21, v21 row_half_mirror row_mask:0xf bank_mask:0xf bound_ctrl:1
	v_add_f32_dpp v22, v22, v22 row_half_mirror row_mask:0xf bank_mask:0xf bound_ctrl:1
	v_add_f32_dpp v23, v23, v23 row_half_mirror row_mask:0xf bank_mask:0xf bound_ctrl:1
	v_add_f32_dpp v20, v24, v24 row_half_mirror row_mask:0xf bank_mask:0xa bound_ctrl:1
	v_add_f32_dpp v21, v25, v25 row_half_mirror row_mask:0xf bank_mask:0xa bound_ctrl:1
	v_add_f32_dpp v22, v26, v26 row_half_mirror row_mask:0xf bank_mask:0xa bound_ctrl:1
	v_add_f32_dpp v23, v27, v27 row_half_mirror row_mask:0xf bank_mask:0xa bound_ctrl:1
	v_add_f32_dpp v20, v20, v20 quad_perm:[1,0,3,2] row_mask:0xf bank_mask:0xf bound_ctrl:1
	v_add_f32_dpp v21, v21, v21 quad_perm:[1,0,3,2] row_mask:0xf bank_mask:0xf bound_ctrl:1
	v_add_f32_dpp v22, v22, v22 quad_perm:[1,0,3,2] row_mask:0xf bank_mask:0xf bound_ctrl:1
	v_add_f32_dpp v23, v23, v23 quad_perm:[1,0,3,2] row_mask:0xf bank_mask:0xf bound_ctrl:1
	v_add_f32_dpp v20, v20, v20 quad_perm:[2,3,0,1] row_mask:0xf bank_mask:0xf bound_ctrl:1
	v_add_f32_dpp v21, v21, v21 quad_perm:[2,3,0,1] row_mask:0xf bank_mask:0xf bound_ctrl:1
	v_add_f32_dpp v22, v22, v22 quad_perm:[2,3,0,1] row_mask:0xf bank_mask:0xf bound_ctrl:1
	v_add_f32_dpp v23, v23, v23 quad_perm:[2,3,0,1] row_mask:0xf bank_mask:0xf bound_ctrl:1
	v_cndmask_b32_e64 v20, v20, v21, s[20:21]
	v_cndmask_b32_e64 v20, v20, v22, s[22:23]
	v_cndmask_b32_e64 v20, v20, v23, s[24:25]
	v_cvt_f16_f32_e32 v81, v20
	global_store_short v80, v81, s[12:13]
	s_sub_u32 s12, s12, 0x8000
	s_subb_u32 s13, s13, 0
.Lscan_noy_d1:
	v_mov_b32_dpp v38, v36 row_newbcast:1 row_mask:0xf bank_mask:0xf
	v_fma_mix_f32 v18, v10, v100, 0 op_sel_hi:[0,1,0]
	v_fma_mix_f32 v14, v10, v94, v10 op_sel_hi:[0,1,0]
	v_fma_mix_f32 v18, v11, v100, v18 op_sel:[0,1,0] op_sel_hi:[0,1,0]
	v_fma_mix_f32 v15, v11, v94, v11 op_sel:[0,1,0] op_sel_hi:[0,1,0]
	v_fma_mix_f32 v18, v12, v101, v18 op_sel_hi:[0,1,0]
	v_fma_mix_f32 v16, v12, v95, v12 op_sel_hi:[0,1,0]
	v_fma_mix_f32 v18, v13, v101, v18 op_sel:[0,1,0] op_sel_hi:[0,1,0]
	v_fma_mix_f32 v17, v13, v95, v13 op_sel:[0,1,0] op_sel_hi:[0,1,0]
	v_fma_mix_f32 v14, v38, v96, v14 op_sel_hi:[1,1,0]
	v_fma_mix_f32 v15, v38, v96, v15 op_sel:[0,1,0] op_sel_hi:[1,1,0]
	v_add_f32_dpp v18, v18, v18 quad_perm:[1,0,3,2] row_mask:0xf bank_mask:0xf bound_ctrl:1
	v_fma_mix_f32 v16, v38, v97, v16 op_sel_hi:[1,1,0]
	v_fma_mix_f32 v17, v38, v97, v17 op_sel:[0,1,0] op_sel_hi:[1,1,0]
	v_add_f32_dpp v18, v18, v18 quad_perm:[2,3,0,1] row_mask:0xf bank_mask:0xf bound_ctrl:1
	v_fma_mix_f32 v20, v10, v92, 0 op_sel_hi:[0,1,0]
	v_fma_mix_f32 v20, v11, v92, v20 op_sel:[0,1,0] op_sel_hi:[0,1,0]
	v_add_f32_dpp v18, v18, v18 row_ror:4 row_mask:0xf bank_mask:0xf bound_ctrl:1
	v_fma_mix_f32 v20, v12, v93, v20 op_sel_hi:[0,1,0]
	v_fma_mix_f32 v20, v13, v93, v20 op_sel:[0,1,0] op_sel_hi:[0,1,0]
	v_add_f32_dpp v18, v18, v18 row_ror:8 row_mask:0xf bank_mask:0xf bound_ctrl:1
	s_waitcnt vmcnt(39)
	global_load_dwordx4 v[84:87], v52, s[6:7]
	v_fma_mix_f32 v10, v18, v98, v14 op_sel_hi:[0,1,0]
	global_load_dwordx2 v[88:89], v52, s[6:7] offset:16
	v_fma_mix_f32 v11, v18, v98, v15 op_sel:[0,1,0] op_sel_hi:[0,1,0]
	global_load_dwordx4 v[90:93], v68, s[8:9]
	v_fma_mix_f32 v12, v18, v99, v16 op_sel_hi:[0,1,0]
	v_fma_mix_f32 v13, v18, v99, v17 op_sel:[0,1,0] op_sel_hi:[0,1,0]
	v_mov_b32_dpp v38, v36 row_newbcast:2 row_mask:0xf bank_mask:0xf
	v_fma_mix_f32 v18, v10, v110, 0 op_sel_hi:[0,1,0]
	v_fma_mix_f32 v14, v10, v104, v10 op_sel_hi:[0,1,0]
	v_fma_mix_f32 v18, v11, v110, v18 op_sel:[0,1,0] op_sel_hi:[0,1,0]
	v_fma_mix_f32 v15, v11, v104, v11 op_sel:[0,1,0] op_sel_hi:[0,1,0]
	v_fma_mix_f32 v18, v12, v111, v18 op_sel_hi:[0,1,0]
	v_fma_mix_f32 v16, v12, v105, v12 op_sel_hi:[0,1,0]
	v_fma_mix_f32 v18, v13, v111, v18 op_sel:[0,1,0] op_sel_hi:[0,1,0]
	v_fma_mix_f32 v17, v13, v105, v13 op_sel:[0,1,0] op_sel_hi:[0,1,0]
	v_fma_mix_f32 v14, v38, v106, v14 op_sel_hi:[1,1,0]
	v_fma_mix_f32 v15, v38, v106, v15 op_sel:[0,1,0] op_sel_hi:[1,1,0]
	v_add_f32_dpp v18, v18, v18 quad_perm:[1,0,3,2] row_mask:0xf bank_mask:0xf bound_ctrl:1
	v_fma_mix_f32 v16, v38, v107, v16 op_sel_hi:[1,1,0]
	v_fma_mix_f32 v17, v38, v107, v17 op_sel:[0,1,0] op_sel_hi:[1,1,0]
	v_add_f32_dpp v18, v18, v18 quad_perm:[2,3,0,1] row_mask:0xf bank_mask:0xf bound_ctrl:1
	v_fma_mix_f32 v21, v10, v102, 0 op_sel_hi:[0,1,0]
	v_fma_mix_f32 v21, v11, v102, v21 op_sel:[0,1,0] op_sel_hi:[0,1,0]
	v_add_f32_dpp v18, v18, v18 row_ror:4 row_mask:0xf bank_mask:0xf bound_ctrl:1
	v_fma_mix_f32 v21, v12, v103, v21 op_sel_hi:[0,1,0]
	v_fma_mix_f32 v21, v13, v103, v21 op_sel:[0,1,0] op_sel_hi:[0,1,0]
	v_add_f32_dpp v18, v18, v18 row_ror:8 row_mask:0xf bank_mask:0xf bound_ctrl:1
	s_waitcnt vmcnt(39)
; __device__ __forceinline__ float row_sum16(float v) { v += __shfl_xor(v, 1); v += __shfl_xor(v, 2); v += __shfl_xor(v, 4); v += __shfl_xor(v, 8); return v; }
; __device__ __forceinline__ float row_sum16(float v) { v += dppf<0xB1>(v); v += dppf<0x4E>(v); v += dppf<0x124>(v); v += dppf<0x128>(v); return v; }
; #define RW_LOAD(slot, step) do { const size_t ro_ = (size_t)row_of(step) * RWW; \
;       s_ok[slot] = *(const h16x8*)((p_rec + ro_ * 3) + urec); s_b[slot] = *(const h16x4*)((p_rec + ro_ * 3) + urec + 8); \
;       s_kr[slot] = *(const h16x8*)((p_sh + ro_ * 2) + ush); s_v[slot] = (p_v + ro_)[uvoff]; } while (0)
; template <int VAR>
; __device__ __forceinline__ void ph_rw_scan(const Params& P) {
;     ...
;         const float vv = (float)s_v[uu];
;         const u32x4 p_ok = __builtin_bit_cast(u32x4, s_ok[uu]), p_kr = __builtin_bit_cast(u32x4, s_kr[uu]);
;         const u32x2 p_bb = __builtin_bit_cast(u32x2, s_b[uu]);
;         const unsigned om0 = p_ok[0], om1 = p_ok[1], kd0 = p_ok[2], kd1 = p_ok[3];
;         const unsigned kk0 = p_kr[0], kk1 = p_kr[1], r0_ = p_kr[2], r1_ = p_kr[3];
;         const unsigned b0_ = p_bb[0], b1_ = p_bb[1];
;         float sa = fmix_lo(S[0], kk0, 0.f); sa = fmix_hi(S[1], kk0, sa);
;         float sb = fmix_lo(S[2], kk1, 0.f); sb = fmix_hi(S[3], kk1, sb);
;         sa = row_sum16(sa + sb);
;         S[0] = fmix_lo(S[0], om0, S[0]); S[1] = fmix_hi(S[1], om0, S[1]); S[2] = fmix_lo(S[2], om1, S[2]); S[3] = fmix_hi(S[3], om1, S[3]);
;         S[0] = fmix_lo(sa, b0_, S[0]); S[1] = fmix_hi(sa, b0_, S[1]); S[2] = fmix_lo(sa, b1_, S[2]); S[3] = fmix_hi(sa, b1_, S[3]);
;         S[0] = fmix_lo(vv, kd0, S[0]); S[1] = fmix_hi(vv, kd0, S[1]); S[2] = fmix_lo(vv, kd1, S[2]); S[3] = fmix_hi(vv, kd1, S[3]);
;         float y = fmix_lo(S[0], r0_, 0.f); y = fmix_hi(S[1], r0_, y);
;         float y2 = fmix_lo(S[2], r1_, 0.f); y2 = fmix_hi(S[3], r1_, y2);
;         y += y2;
;         if (VAR == 0 && islat) {
;           y = row_sum16(y);
;           if (q == 0) yout[((size_t)dir * NL + row_of(t0 + uu)) * RWW + hh * 64 + vrow] = (h16)y;
;         }
;         if (VAR != 0) asm volatile("" :: "v"(y));
;         const int nstep = t0 + uu + RW_U < RW_NS ? t0 + uu + RW_U : RW_NS - 1;
;         if (VAR != 2) RW_LOAD(uu, nstep);
	global_load_dwordx4 v[94:97], v53, s[6:7]
	v_fma_mix_f32 v10, v18, v108, v14 op_sel_hi:[0,1,0]
	global_load_dwordx2 v[98:99], v53, s[6:7] offset:16
	v_fma_mix_f32 v11, v18, v108, v15 op_sel:[0,1,0] op_sel_hi:[0,1,0]
	global_load_dwordx4 v[100:103], v68, s[8:9] offset:-4096
	v_fma_mix_f32 v12, v18, v109, v16 op_sel_hi:[0,1,0]
	v_fma_mix_f32 v13, v18, v109, v17 op_sel:[0,1,0] op_sel_hi:[0,1,0]
	v_mov_b32_dpp v38, v36 row_newbcast:3 row_mask:0xf bank_mask:0xf
	v_fma_mix_f32 v18, v10, v120, 0 op_sel_hi:[0,1,0]
	v_fma_mix_f32 v14, v10, v114, v10 op_sel_hi:[0,1,0]
	v_fma_mix_f32 v18, v11, v120, v18 op_sel:[0,1,0] op_sel_hi:[0,1,0]
	v_fma_mix_f32 v15, v11, v114, v11 op_sel:[0,1,0] op_sel_hi:[0,1,0]
	v_fma_mix_f32 v18, v12, v121, v18 op_sel_hi:[0,1,0]
	v_fma_mix_f32 v16, v12, v115, v12 op_sel_hi:[0,1,0]
	v_fma_mix_f32 v18, v13, v121, v18 op_sel:[0,1,0] op_sel_hi:[0,1,0]
	v_fma_mix_f32 v17, v13, v115, v13 op_sel:[0,1,0] op_sel_hi:[0,1,0]
	v_fma_mix_f32 v14, v38, v116, v14 op_sel_hi:[1,1,0]
	v_fma_mix_f32 v15, v38, v116, v15 op_sel:[0,1,0] op_sel_hi:[1,1,0]
	v_add_f32_dpp v18, v18, v18 quad_perm:[1,0,3,2] row_mask:0xf bank_mask:0xf bound_ctrl:1
	v_fma_mix_f32 v16, v38, v117, v16 op_sel_hi:[1,1,0]
	v_fma_mix_f32 v17, v38, v117, v17 op_sel:[0,1,0] op_sel_hi:[1,1,0]
	v_add_f32_dpp v18, v18, v18 quad_perm:[2,3,0,1] row_mask:0xf bank_mask:0xf bound_ctrl:1
	v_fma_mix_f32 v22, v10, v112, 0 op_sel_hi:[0,1,0]
	v_fma_mix_f32 v22, v11, v112, v22 op_sel:[0,1,0] op_sel_hi:[0,1,0]
	v_add_f32_dpp v18, v18, v18 row_ror:4 row_mask:0xf bank_mask:0xf bound_ctrl:1
	v_fma_mix_f32 v22, v12, v113, v22 op_sel_hi:[0,1,0]
	v_fma_mix_f32 v22, v13, v113, v22 op_sel:[0,1,0] op_sel_hi:[0,1,0]
	v_add_f32_dpp v18, v18, v18 row_ror:8 row_mask:0xf bank_mask:0xf bound_ctrl:1
	s_waitcnt vmcnt(39)
	global_load_dwordx4 v[104:107], v54, s[6:7]
	v_fma_mix_f32 v10, v18, v118, v14 op_sel_hi:[0,1,0]
	global_load_dwordx2 v[108:109], v54, s[6:7] offset:16
	v_fma_mix_f32 v11, v18, v118, v15 op_sel:[0,1,0] op_sel_hi:[0,1,0]
	global_load_dwordx4 v[110:113], v69, s[8:9]
	v_fma_mix_f32 v12, v18, v119, v16 op_sel_hi:[0,1,0]
	v_fma_mix_f32 v13, v18, v119, v17 op_sel:[0,1,0] op_sel_hi:[0,1,0]
	v_mov_b32_dpp v38, v36 row_newbcast:4 row_mask:0xf bank_mask:0xf
	v_fma_mix_f32 v18, v10, v130, 0 op_sel_hi:[0,1,0]
	v_fma_mix_f32 v14, v10, v124, v10 op_sel_hi:[0,1,0]
	v_fma_mix_f32 v18, v11, v130, v18 op_sel:[0,1,0] op_sel_hi:[0,1,0]
	v_fma_mix_f32 v15, v11, v124, v11 op_sel:[0,1,0] op_sel_hi:[0,1,0]
	v_fma_mix_f32 v18, v12, v131, v18 op_sel_hi:[0,1,0]
	v_fma_mix_f32 v16, v12, v125, v12 op_sel_hi:[0,1,0]
	v_fma_mix_f32 v18, v13, v131, v18 op_sel:[0,1,0] op_sel_hi:[0,1,0]
	v_fma_mix_f32 v17, v13, v125, v13 op_sel:[0,1,0] op_sel_hi:[0,1,0]
	v_fma_mix_f32 v14, v38, v126, v14 op_sel_hi:[1,1,0]
	v_fma_mix_f32 v15, v38, v126, v15 op_sel:[0,1,0] op_sel_hi:[1,1,0]
	v_add_f32_dpp v18, v18, v18 quad_perm:[1,0,3,2] row_mask:0xf bank_mask:0xf bound_ctrl:1
	v_fma_mix_f32 v16, v38, v127, v16 op_sel_hi:[1,1,0]
	v_fma_mix_f32 v17, v38, v127, v17 op_sel:[0,1,0] op_sel_hi:[1,1,0]
	v_add_f32_dpp v18, v18, v18 quad_perm:[2,3,0,1] row_mask:0xf bank_mask:0xf bound_ctrl:1
	v_fma_mix_f32 v23, v10, v122, 0 op_sel_hi:[0,1,0]
	v_fma_mix_f32 v23, v11, v122, v23 op_sel:[0,1,0] op_sel_hi:[0,1,0]
	v_add_f32_dpp v18, v18, v18 row_ror:4 row_mask:0xf bank_mask:0xf bound_ctrl:1
	v_fma_mix_f32 v23, v12, v123, v23 op_sel_hi:[0,1,0]
	v_fma_mix_f32 v23, v13, v123, v23 op_sel:[0,1,0] op_sel_hi:[0,1,0]
	v_add_f32_dpp v18, v18, v18 row_ror:8 row_mask:0xf bank_mask:0xf bound_ctrl:1
	s_waitcnt vmcnt(39)
	global_load_dwordx4 v[114:117], v55, s[6:7]
	v_fma_mix_f32 v10, v18, v128, v14 op_sel_hi:[0,1,0]
	global_load_dwordx2 v[118:119], v55, s[6:7] offset:16
	v_fma_mix_f32 v11, v18, v128, v15 op_sel:[0,1,0] op_sel_hi:[0,1,0]
	global_load_dwordx4 v[120:123], v69, s[8:9] offset:-4096
	v_fma_mix_f32 v12, v18, v129, v16 op_sel_hi:[0,1,0]
	v_fma_mix_f32 v13, v18, v129, v17 op_sel:[0,1,0] op_sel_hi:[0,1,0]
	v_mov_b32_dpp v38, v36 row_newbcast:5 row_mask:0xf bank_mask:0xf
	v_fma_mix_f32 v18, v10, v140, 0 op_sel_hi:[0,1,0]
	v_fma_mix_f32 v14, v10, v134, v10 op_sel_hi:[0,1,0]
	v_fma_mix_f32 v18, v11, v140, v18 op_sel:[0,1,0] op_sel_hi:[0,1,0]
	v_fma_mix_f32 v15, v11, v134, v11 op_sel:[0,1,0] op_sel_hi:[0,1,0]
	v_fma_mix_f32 v18, v12, v141, v18 op_sel_hi:[0,1,0]
	v_fma_mix_f32 v16, v12, v135, v12 op_sel_hi:[0,1,0]
	v_fma_mix_f32 v18, v13, v141, v18 op_sel:[0,1,0] op_sel_hi:[0,1,0]
	v_fma_mix_f32 v17, v13, v135, v13 op_sel:[0,1,0] op_sel_hi:[0,1,0]
	v_fma_mix_f32 v14, v38, v136, v14 op_sel_hi:[1,1,0]
	v_fma_mix_f32 v15, v38, v136, v15 op_sel:[0,1,0] op_sel_hi:[1,1,0]
	v_add_f32_dpp v18, v18, v18 quad_perm:[1,0,3,2] row_mask:0xf bank_mask:0xf bound_ctrl:1
	v_fma_mix_f32 v16, v38, v137, v16 op_sel_hi:[1,1,0]
	v_fma_mix_f32 v17, v38, v137, v17 op_sel:[0,1,0] op_sel_hi:[1,1,0]
	v_add_f32_dpp v18, v18, v18 quad_perm:[2,3,0,1] row_mask:0xf bank_mask:0xf bound_ctrl:1
	v_fma_mix_f32 v24, v10, v132, 0 op_sel_hi:[0,1,0]
	v_fma_mix_f32 v24, v11, v132, v24 op_sel:[0,1,0] op_sel_hi:[0,1,0]
	v_add_f32_dpp v18, v18, v18 row_ror:4 row_mask:0xf bank_mask:0xf bound_ctrl:1
	v_fma_mix_f32 v24, v12, v133, v24 op_sel_hi:[0,1,0]
	v_fma_mix_f32 v24, v13, v133, v24 op_sel:[0,1,0] op_sel_hi:[0,1,0]
	v_add_f32_dpp v18, v18, v18 row_ror:8 row_mask:0xf bank_mask:0xf bound_ctrl:1
	s_waitcnt vmcnt(39)
; __device__ __forceinline__ float row_sum16(float v) { v += __shfl_xor(v, 1); v += __shfl_xor(v, 2); v += __shfl_xor(v, 4); v += __shfl_xor(v, 8); return v; }
; __device__ __forceinline__ float row_sum16(float v) { v += dppf<0xB1>(v); v += dppf<0x4E>(v); v += dppf<0x124>(v); v += dppf<0x128>(v); return v; }
; #define RW_LOAD(slot, step) do { const size_t ro_ = (size_t)row_of(step) * RWW; \
;       s_ok[slot] = *(const h16x8*)((p_rec + ro_ * 3) + urec); s_b[slot] = *(const h16x4*)((p_rec + ro_ * 3) + urec + 8); \
;       s_kr[slot] = *(const h16x8*)((p_sh + ro_ * 2) + ush); s_v[slot] = (p_v + ro_)[uvoff]; } while (0)
; template <int VAR>
; __device__ __forceinline__ void ph_rw_scan(const Params& P) {
;     ...
;         const float vv = (float)s_v[uu];
;         const u32x4 p_ok = __builtin_bit_cast(u32x4, s_ok[uu]), p_kr = __builtin_bit_cast(u32x4, s_kr[uu]);
;         const u32x2 p_bb = __builtin_bit_cast(u32x2, s_b[uu]);
;         const unsigned om0 = p_ok[0], om1 = p_ok[1], kd0 = p_ok[2], kd1 = p_ok[3];
;         const unsigned kk0 = p_kr[0], kk1 = p_kr[1], r0_ = p_kr[2], r1_ = p_kr[3];
;         const unsigned b0_ = p_bb[0], b1_ = p_bb[1];
;         float sa = fmix_lo(S[0], kk0, 0.f); sa = fmix_hi(S[1], kk0, sa);
;         float sb = fmix_lo(S[2], kk1, 0.f); sb = fmix_hi(S[3], kk1, sb);
;         sa = row_sum16(sa + sb);
;         S[0] = fmix_lo(S[0], om0, S[0]); S[1] = fmix_hi(S[1], om0, S[1]); S[2] = fmix_lo(S[2], om1, S[2]); S[3] = fmix_hi(S[3], om1, S[3]);
;         S[0] = fmix_lo(sa, b0_, S[0]); S[1] = fmix_hi(sa, b0_, S[1]); S[2] = fmix_lo(sa, b1_, S[2]); S[3] = fmix_hi(sa, b1_, S[3]);
;         S[0] = fmix_lo(vv, kd0, S[0]); S[1] = fmix_hi(vv, kd0, S[1]); S[2] = fmix_lo(vv, kd1, S[2]); S[3] = fmix_hi(vv, kd1, S[3]);
;         float y = fmix_lo(S[0], r0_, 0.f); y = fmix_hi(S[1], r0_, y);
;         float y2 = fmix_lo(S[2], r1_, 0.f); y2 = fmix_hi(S[3], r1_, y2);
;         y += y2;
;         if (VAR == 0 && islat) {
;           y = row_sum16(y);
;           if (q == 0) yout[((size_t)dir * NL + row_of(t0 + uu)) * RWW + hh * 64 + vrow] = (h16)y;
;         }
;         if (VAR != 0) asm volatile("" :: "v"(y));
;         const int nstep = t0 + uu + RW_U < RW_NS ? t0 + uu + RW_U : RW_NS - 1;
;         if (VAR != 2) RW_LOAD(uu, nstep);
	global_load_dwordx4 v[124:127], v56, s[6:7]
	v_fma_mix_f32 v10, v18, v138, v14 op_sel_hi:[0,1,0]
	global_load_dwordx2 v[128:129], v56, s[6:7] offset:16
	v_fma_mix_f32 v11, v18, v138, v15 op_sel:[0,1,0] op_sel_hi:[0,1,0]
	global_load_dwordx4 v[130:133], v70, s[8:9]
	v_fma_mix_f32 v12, v18, v139, v16 op_sel_hi:[0,1,0]
	v_fma_mix_f32 v13, v18, v139, v17 op_sel:[0,1,0] op_sel_hi:[0,1,0]
	v_mov_b32_dpp v38, v36 row_newbcast:6 row_mask:0xf bank_mask:0xf
	v_fma_mix_f32 v18, v10, v150, 0 op_sel_hi:[0,1,0]
	v_fma_mix_f32 v14, v10, v144, v10 op_sel_hi:[0,1,0]
	v_fma_mix_f32 v18, v11, v150, v18 op_sel:[0,1,0] op_sel_hi:[0,1,0]
	v_fma_mix_f32 v15, v11, v144, v11 op_sel:[0,1,0] op_sel_hi:[0,1,0]
	v_fma_mix_f32 v18, v12, v151, v18 op_sel_hi:[0,1,0]
	v_fma_mix_f32 v16, v12, v145, v12 op_sel_hi:[0,1,0]
	v_fma_mix_f32 v18, v13, v151, v18 op_sel:[0,1,0] op_sel_hi:[0,1,0]
	v_fma_mix_f32 v17, v13, v145, v13 op_sel:[0,1,0] op_sel_hi:[0,1,0]
	v_fma_mix_f32 v14, v38, v146, v14 op_sel_hi:[1,1,0]
	v_fma_mix_f32 v15, v38, v146, v15 op_sel:[0,1,0] op_sel_hi:[1,1,0]
	v_add_f32_dpp v18, v18, v18 quad_perm:[1,0,3,2] row_mask:0xf bank_mask:0xf bound_ctrl:1
	v_fma_mix_f32 v16, v38, v147, v16 op_sel_hi:[1,1,0]
	v_fma_mix_f32 v17, v38, v147, v17 op_sel:[0,1,0] op_sel_hi:[1,1,0]
	v_add_f32_dpp v18, v18, v18 quad_perm:[2,3,0,1] row_mask:0xf bank_mask:0xf bound_ctrl:1
	v_fma_mix_f32 v25, v10, v142, 0 op_sel_hi:[0,1,0]
	v_fma_mix_f32 v25, v11, v142, v25 op_sel:[0,1,0] op_sel_hi:[0,1,0]
	v_add_f32_dpp v18, v18, v18 row_ror:4 row_mask:0xf bank_mask:0xf bound_ctrl:1
	v_fma_mix_f32 v25, v12, v143, v25 op_sel_hi:[0,1,0]
	v_fma_mix_f32 v25, v13, v143, v25 op_sel:[0,1,0] op_sel_hi:[0,1,0]
	v_add_f32_dpp v18, v18, v18 row_ror:8 row_mask:0xf bank_mask:0xf bound_ctrl:1
	s_waitcnt vmcnt(39)
	global_load_dwordx4 v[134:137], v57, s[6:7]
	v_fma_mix_f32 v10, v18, v148, v14 op_sel_hi:[0,1,0]
	global_load_dwordx2 v[138:139], v57, s[6:7] offset:16
	v_fma_mix_f32 v11, v18, v148, v15 op_sel:[0,1,0] op_sel_hi:[0,1,0]
	global_load_dwordx4 v[140:143], v70, s[8:9] offset:-4096
	v_fma_mix_f32 v12, v18, v149, v16 op_sel_hi:[0,1,0]
	v_fma_mix_f32 v13, v18, v149, v17 op_sel:[0,1,0] op_sel_hi:[0,1,0]
	v_mov_b32_dpp v38, v36 row_newbcast:7 row_mask:0xf bank_mask:0xf
	v_fma_mix_f32 v18, v10, v160, 0 op_sel_hi:[0,1,0]
	v_fma_mix_f32 v14, v10, v154, v10 op_sel_hi:[0,1,0]
	v_fma_mix_f32 v18, v11, v160, v18 op_sel:[0,1,0] op_sel_hi:[0,1,0]
	v_fma_mix_f32 v15, v11, v154, v11 op_sel:[0,1,0] op_sel_hi:[0,1,0]
	v_fma_mix_f32 v18, v12, v161, v18 op_sel_hi:[0,1,0]
	v_fma_mix_f32 v16, v12, v155, v12 op_sel_hi:[0,1,0]
	v_fma_mix_f32 v18, v13, v161, v18 op_sel:[0,1,0] op_sel_hi:[0,1,0]
	v_fma_mix_f32 v17, v13, v155, v13 op_sel:[0,1,0] op_sel_hi:[0,1,0]
	v_fma_mix_f32 v14, v38, v156, v14 op_sel_hi:[1,1,0]
	v_fma_mix_f32 v15, v38, v156, v15 op_sel:[0,1,0] op_sel_hi:[1,1,0]
	v_add_f32_dpp v18, v18, v18 quad_perm:[1,0,3,2] row_mask:0xf bank_mask:0xf bound_ctrl:1
	v_fma_mix_f32 v16, v38, v157, v16 op_sel_hi:[1,1,0]
	v_fma_mix_f32 v17, v38, v157, v17 op_sel:[0,1,0] op_sel_hi:[1,1,0]
	v_add_f32_dpp v18, v18, v18 quad_perm:[2,3,0,1] row_mask:0xf bank_mask:0xf bound_ctrl:1
	v_fma_mix_f32 v26, v10, v152, 0 op_sel_hi:[0,1,0]
	v_fma_mix_f32 v26, v11, v152, v26 op_sel:[0,1,0] op_sel_hi:[0,1,0]
	v_add_f32_dpp v18, v18, v18 row_ror:4 row_mask:0xf bank_mask:0xf bound_ctrl:1
	v_fma_mix_f32 v26, v12, v153, v26 op_sel_hi:[0,1,0]
	v_fma_mix_f32 v26, v13, v153, v26 op_sel:[0,1,0] op_sel_hi:[0,1,0]
	v_add_f32_dpp v18, v18, v18 row_ror:8 row_mask:0xf bank_mask:0xf bound_ctrl:1
	s_waitcnt vmcnt(39)
	global_load_dwordx4 v[144:147], v58, s[6:7]
	v_fma_mix_f32 v10, v18, v158, v14 op_sel_hi:[0,1,0]
	global_load_dwordx2 v[148:149], v58, s[6:7] offset:16
	v_fma_mix_f32 v11, v18, v158, v15 op_sel:[0,1,0] op_sel_hi:[0,1,0]
	global_load_dwordx4 v[150:153], v71, s[8:9]
	v_fma_mix_f32 v12, v18, v159, v16 op_sel_hi:[0,1,0]
	v_fma_mix_f32 v13, v18, v159, v17 op_sel:[0,1,0] op_sel_hi:[0,1,0]
	v_mov_b32_dpp v38, v36 row_newbcast:8 row_mask:0xf bank_mask:0xf
	v_fma_mix_f32 v18, v10, v170, 0 op_sel_hi:[0,1,0]
	v_fma_mix_f32 v14, v10, v164, v10 op_sel_hi:[0,1,0]
	v_fma_mix_f32 v18, v11, v170, v18 op_sel:[0,1,0] op_sel_hi:[0,1,0]
	v_fma_mix_f32 v15, v11, v164, v11 op_sel:[0,1,0] op_sel_hi:[0,1,0]
	v_fma_mix_f32 v18, v12, v171, v18 op_sel_hi:[0,1,0]
	v_fma_mix_f32 v16, v12, v165, v12 op_sel_hi:[0,1,0]
	v_fma_mix_f32 v18, v13, v171, v18 op_sel:[0,1,0] op_sel_hi:[0,1,0]
	v_fma_mix_f32 v17, v13, v165, v13 op_sel:[0,1,0] op_sel_hi:[0,1,0]
	v_fma_mix_f32 v14, v38, v166, v14 op_sel_hi:[1,1,0]
	v_fma_mix_f32 v15, v38, v166, v15 op_sel:[0,1,0] op_sel_hi:[1,1,0]
	v_add_f32_dpp v18, v18, v18 quad_perm:[1,0,3,2] row_mask:0xf bank_mask:0xf bound_ctrl:1
	v_fma_mix_f32 v16, v38, v167, v16 op_sel_hi:[1,1,0]
	v_fma_mix_f32 v17, v38, v167, v17 op_sel:[0,1,0] op_sel_hi:[1,1,0]
	v_add_f32_dpp v18, v18, v18 quad_perm:[2,3,0,1] row_mask:0xf bank_mask:0xf bound_ctrl:1
	v_fma_mix_f32 v27, v10, v162, 0 op_sel_hi:[0,1,0]
	v_fma_mix_f32 v27, v11, v162, v27 op_sel:[0,1,0] op_sel_hi:[0,1,0]
	v_add_f32_dpp v18, v18, v18 row_ror:4 row_mask:0xf bank_mask:0xf bound_ctrl:1
	v_fma_mix_f32 v27, v12, v163, v27 op_sel_hi:[0,1,0]
	v_fma_mix_f32 v27, v13, v163, v27 op_sel:[0,1,0] op_sel_hi:[0,1,0]
	v_add_f32_dpp v18, v18, v18 row_ror:8 row_mask:0xf bank_mask:0xf bound_ctrl:1
	s_waitcnt vmcnt(39)
; __device__ __forceinline__ float row_sum16(float v) { v += __shfl_xor(v, 1); v += __shfl_xor(v, 2); v += __shfl_xor(v, 4); v += __shfl_xor(v, 8); return v; }
; __device__ __forceinline__ float row_sum16(float v) { v += dppf<0xB1>(v); v += dppf<0x4E>(v); v += dppf<0x124>(v); v += dppf<0x128>(v); return v; }
; #define RW_LOAD(slot, step) do { const size_t ro_ = (size_t)row_of(step) * RWW; \
;       s_ok[slot] = *(const h16x8*)((p_rec + ro_ * 3) + urec); s_b[slot] = *(const h16x4*)((p_rec + ro_ * 3) + urec + 8); \
;       s_kr[slot] = *(const h16x8*)((p_sh + ro_ * 2) + ush); s_v[slot] = (p_v + ro_)[uvoff]; } while (0)
; template <int VAR>
; __device__ __forceinline__ void ph_rw_scan(const Params& P) {
;     ...
;         const float vv = (float)s_v[uu];
;         const u32x4 p_ok = __builtin_bit_cast(u32x4, s_ok[uu]), p_kr = __builtin_bit_cast(u32x4, s_kr[uu]);
;         const u32x2 p_bb = __builtin_bit_cast(u32x2, s_b[uu]);
;         const unsigned om0 = p_ok[0], om1 = p_ok[1], kd0 = p_ok[2], kd1 = p_ok[3];
;         const unsigned kk0 = p_kr[0], kk1 = p_kr[1], r0_ = p_kr[2], r1_ = p_kr[3];
;         const unsigned b0_ = p_bb[0], b1_ = p_bb[1];
;         float sa = fmix_lo(S[0], kk0, 0.f); sa = fmix_hi(S[1], kk0, sa);
;         float sb = fmix_lo(S[2], kk1, 0.f); sb = fmix_hi(S[3], kk1, sb);
;         sa = row_sum16(sa + sb);
;         S[0] = fmix_lo(S[0], om0, S[0]); S[1] = fmix_hi(S[1], om0, S[1]); S[2] = fmix_lo(S[2], om1, S[2]); S[3] = fmix_hi(S[3], om1, S[3]);
;         S[0] = fmix_lo(sa, b0_, S[0]); S[1] = fmix_hi(sa, b0_, S[1]); S[2] = fmix_lo(sa, b1_, S[2]); S[3] = fmix_hi(sa, b1_, S[3]);
;         S[0] = fmix_lo(vv, kd0, S[0]); S[1] = fmix_hi(vv, kd0, S[1]); S[2] = fmix_lo(vv, kd1, S[2]); S[3] = fmix_hi(vv, kd1, S[3]);
;         float y = fmix_lo(S[0], r0_, 0.f); y = fmix_hi(S[1], r0_, y);
;         float y2 = fmix_lo(S[2], r1_, 0.f); y2 = fmix_hi(S[3], r1_, y2);
;         y += y2;
;         if (VAR == 0 && islat) {
;           y = row_sum16(y);
;           if (q == 0) yout[((size_t)dir * NL + row_of(t0 + uu)) * RWW + hh * 64 + vrow] = (h16)y;
;         }
;         if (VAR != 0) asm volatile("" :: "v"(y));
;         const int nstep = t0 + uu + RW_U < RW_NS ? t0 + uu + RW_U : RW_NS - 1;
;         if (VAR != 2) RW_LOAD(uu, nstep);
	global_load_dwordx4 v[154:157], v59, s[6:7]
	v_fma_mix_f32 v10, v18, v168, v14 op_sel_hi:[0,1,0]
	global_load_dwordx2 v[158:159], v59, s[6:7] offset:16
	v_fma_mix_f32 v11, v18, v168, v15 op_sel:[0,1,0] op_sel_hi:[0,1,0]
	global_load_dwordx4 v[160:163], v71, s[8:9] offset:-4096
	v_fma_mix_f32 v12, v18, v169, v16 op_sel_hi:[0,1,0]
	v_fma_mix_f32 v13, v18, v169, v17 op_sel:[0,1,0] op_sel_hi:[0,1,0]
	v_mov_b32_dpp v38, v36 row_newbcast:9 row_mask:0xf bank_mask:0xf
	v_fma_mix_f32 v18, v10, v180, 0 op_sel_hi:[0,1,0]
	v_fma_mix_f32 v14, v10, v174, v10 op_sel_hi:[0,1,0]
	v_fma_mix_f32 v18, v11, v180, v18 op_sel:[0,1,0] op_sel_hi:[0,1,0]
	v_fma_mix_f32 v15, v11, v174, v11 op_sel:[0,1,0] op_sel_hi:[0,1,0]
	v_fma_mix_f32 v18, v12, v181, v18 op_sel_hi:[0,1,0]
	v_fma_mix_f32 v16, v12, v175, v12 op_sel_hi:[0,1,0]
	v_fma_mix_f32 v18, v13, v181, v18 op_sel:[0,1,0] op_sel_hi:[0,1,0]
	v_fma_mix_f32 v17, v13, v175, v13 op_sel:[0,1,0] op_sel_hi:[0,1,0]
	v_fma_mix_f32 v14, v38, v176, v14 op_sel_hi:[1,1,0]
	v_fma_mix_f32 v15, v38, v176, v15 op_sel:[0,1,0] op_sel_hi:[1,1,0]
	v_add_f32_dpp v18, v18, v18 quad_perm:[1,0,3,2] row_mask:0xf bank_mask:0xf bound_ctrl:1
	v_fma_mix_f32 v16, v38, v177, v16 op_sel_hi:[1,1,0]
	v_fma_mix_f32 v17, v38, v177, v17 op_sel:[0,1,0] op_sel_hi:[1,1,0]
	v_add_f32_dpp v18, v18, v18 quad_perm:[2,3,0,1] row_mask:0xf bank_mask:0xf bound_ctrl:1
	v_fma_mix_f32 v28, v10, v172, 0 op_sel_hi:[0,1,0]
	v_fma_mix_f32 v28, v11, v172, v28 op_sel:[0,1,0] op_sel_hi:[0,1,0]
	v_add_f32_dpp v18, v18, v18 row_ror:4 row_mask:0xf bank_mask:0xf bound_ctrl:1
	v_fma_mix_f32 v28, v12, v173, v28 op_sel_hi:[0,1,0]
	v_fma_mix_f32 v28, v13, v173, v28 op_sel:[0,1,0] op_sel_hi:[0,1,0]
	v_add_f32_dpp v18, v18, v18 row_ror:8 row_mask:0xf bank_mask:0xf bound_ctrl:1
	s_waitcnt vmcnt(39)
	global_load_dwordx4 v[164:167], v60, s[6:7]
	v_fma_mix_f32 v10, v18, v178, v14 op_sel_hi:[0,1,0]
	global_load_dwordx2 v[168:169], v60, s[6:7] offset:16
	v_fma_mix_f32 v11, v18, v178, v15 op_sel:[0,1,0] op_sel_hi:[0,1,0]
	global_load_dwordx4 v[170:173], v72, s[8:9]
	v_fma_mix_f32 v12, v18, v179, v16 op_sel_hi:[0,1,0]
	v_fma_mix_f32 v13, v18, v179, v17 op_sel:[0,1,0] op_sel_hi:[0,1,0]
	v_mov_b32_dpp v38, v36 row_newbcast:10 row_mask:0xf bank_mask:0xf
	v_fma_mix_f32 v18, v10, v190, 0 op_sel_hi:[0,1,0]
	v_fma_mix_f32 v14, v10, v184, v10 op_sel_hi:[0,1,0]
	v_fma_mix_f32 v18, v11, v190, v18 op_sel:[0,1,0] op_sel_hi:[0,1,0]
	v_fma_mix_f32 v15, v11, v184, v11 op_sel:[0,1,0] op_sel_hi:[0,1,0]
	v_fma_mix_f32 v18, v12, v191, v18 op_sel_hi:[0,1,0]
	v_fma_mix_f32 v16, v12, v185, v12 op_sel_hi:[0,1,0]
	v_fma_mix_f32 v18, v13, v191, v18 op_sel:[0,1,0] op_sel_hi:[0,1,0]
	v_fma_mix_f32 v17, v13, v185, v13 op_sel:[0,1,0] op_sel_hi:[0,1,0]
	v_fma_mix_f32 v14, v38, v186, v14 op_sel_hi:[1,1,0]
	v_fma_mix_f32 v15, v38, v186, v15 op_sel:[0,1,0] op_sel_hi:[1,1,0]
	v_add_f32_dpp v18, v18, v18 quad_perm:[1,0,3,2] row_mask:0xf bank_mask:0xf bound_ctrl:1
	v_fma_mix_f32 v16, v38, v187, v16 op_sel_hi:[1,1,0]
	v_fma_mix_f32 v17, v38, v187, v17 op_sel:[0,1,0] op_sel_hi:[1,1,0]
	v_add_f32_dpp v18, v18, v18 quad_perm:[2,3,0,1] row_mask:0xf bank_mask:0xf bound_ctrl:1
	v_fma_mix_f32 v29, v10, v182, 0 op_sel_hi:[0,1,0]
	v_fma_mix_f32 v29, v11, v182, v29 op_sel:[0,1,0] op_sel_hi:[0,1,0]
	v_add_f32_dpp v18, v18, v18 row_ror:4 row_mask:0xf bank_mask:0xf bound_ctrl:1
	v_fma_mix_f32 v29, v12, v183, v29 op_sel_hi:[0,1,0]
	v_fma_mix_f32 v29, v13, v183, v29 op_sel:[0,1,0] op_sel_hi:[0,1,0]
	v_add_f32_dpp v18, v18, v18 row_ror:8 row_mask:0xf bank_mask:0xf bound_ctrl:1
	s_waitcnt vmcnt(39)
	global_load_dwordx4 v[174:177], v61, s[6:7]
	v_fma_mix_f32 v10, v18, v188, v14 op_sel_hi:[0,1,0]
	global_load_dwordx2 v[178:179], v61, s[6:7] offset:16
	v_fma_mix_f32 v11, v18, v188, v15 op_sel:[0,1,0] op_sel_hi:[0,1,0]
	global_load_dwordx4 v[180:183], v72, s[8:9] offset:-4096
	v_fma_mix_f32 v12, v18, v189, v16 op_sel_hi:[0,1,0]
	v_fma_mix_f32 v13, v18, v189, v17 op_sel:[0,1,0] op_sel_hi:[0,1,0]
	v_mov_b32_dpp v38, v36 row_newbcast:11 row_mask:0xf bank_mask:0xf
	v_fma_mix_f32 v18, v10, v200, 0 op_sel_hi:[0,1,0]
	v_fma_mix_f32 v14, v10, v194, v10 op_sel_hi:[0,1,0]
	v_fma_mix_f32 v18, v11, v200, v18 op_sel:[0,1,0] op_sel_hi:[0,1,0]
	v_fma_mix_f32 v15, v11, v194, v11 op_sel:[0,1,0] op_sel_hi:[0,1,0]
	v_fma_mix_f32 v18, v12, v201, v18 op_sel_hi:[0,1,0]
	v_fma_mix_f32 v16, v12, v195, v12 op_sel_hi:[0,1,0]
	v_fma_mix_f32 v18, v13, v201, v18 op_sel:[0,1,0] op_sel_hi:[0,1,0]
	v_fma_mix_f32 v17, v13, v195, v13 op_sel:[0,1,0] op_sel_hi:[0,1,0]
	v_fma_mix_f32 v14, v38, v196, v14 op_sel_hi:[1,1,0]
	v_fma_mix_f32 v15, v38, v196, v15 op_sel:[0,1,0] op_sel_hi:[1,1,0]
	v_add_f32_dpp v18, v18, v18 quad_perm:[1,0,3,2] row_mask:0xf bank_mask:0xf bound_ctrl:1
	v_fma_mix_f32 v16, v38, v197, v16 op_sel_hi:[1,1,0]
	v_fma_mix_f32 v17, v38, v197, v17 op_sel:[0,1,0] op_sel_hi:[1,1,0]
	v_add_f32_dpp v18, v18, v18 quad_perm:[2,3,0,1] row_mask:0xf bank_mask:0xf bound_ctrl:1
	v_fma_mix_f32 v30, v10, v192, 0 op_sel_hi:[0,1,0]
	v_fma_mix_f32 v30, v11, v192, v30 op_sel:[0,1,0] op_sel_hi:[0,1,0]
	v_add_f32_dpp v18, v18, v18 row_ror:4 row_mask:0xf bank_mask:0xf bound_ctrl:1
	v_fma_mix_f32 v30, v12, v193, v30 op_sel_hi:[0,1,0]
	v_fma_mix_f32 v30, v13, v193, v30 op_sel:[0,1,0] op_sel_hi:[0,1,0]
	v_add_f32_dpp v18, v18, v18 row_ror:8 row_mask:0xf bank_mask:0xf bound_ctrl:1
	s_waitcnt vmcnt(39)
; __device__ __forceinline__ float row_sum16(float v) { v += __shfl_xor(v, 1); v += __shfl_xor(v, 2); v += __shfl_xor(v, 4); v += __shfl_xor(v, 8); return v; }
; __device__ __forceinline__ float row_sum16(float v) { v += dppf<0xB1>(v); v += dppf<0x4E>(v); v += dppf<0x124>(v); v += dppf<0x128>(v); return v; }
; #define RW_LOAD(slot, step) do { const size_t ro_ = (size_t)row_of(step) * RWW; \
;       s_ok[slot] = *(const h16x8*)((p_rec + ro_ * 3) + urec); s_b[slot] = *(const h16x4*)((p_rec + ro_ * 3) + urec + 8); \
;       s_kr[slot] = *(const h16x8*)((p_sh + ro_ * 2) + ush); s_v[slot] = (p_v + ro_)[uvoff]; } while (0)
; template <int VAR>
; __device__ __forceinline__ void ph_rw_scan(const Params& P) {
;     ...
;         const float vv = (float)s_v[uu];
;         const u32x4 p_ok = __builtin_bit_cast(u32x4, s_ok[uu]), p_kr = __builtin_bit_cast(u32x4, s_kr[uu]);
;         const u32x2 p_bb = __builtin_bit_cast(u32x2, s_b[uu]);
;         const unsigned om0 = p_ok[0], om1 = p_ok[1], kd0 = p_ok[2], kd1 = p_ok[3];
;         const unsigned kk0 = p_kr[0], kk1 = p_kr[1], r0_ = p_kr[2], r1_ = p_kr[3];
;         const unsigned b0_ = p_bb[0], b1_ = p_bb[1];
;         float sa = fmix_lo(S[0], kk0, 0.f); sa = fmix_hi(S[1], kk0, sa);
;         float sb = fmix_lo(S[2], kk1, 0.f); sb = fmix_hi(S[3], kk1, sb);
;         sa = row_sum16(sa + sb);
;         S[0] = fmix_lo(S[0], om0, S[0]); S[1] = fmix_hi(S[1], om0, S[1]); S[2] = fmix_lo(S[2], om1, S[2]); S[3] = fmix_hi(S[3], om1, S[3]);
;         S[0] = fmix_lo(sa, b0_, S[0]); S[1] = fmix_hi(sa, b0_, S[1]); S[2] = fmix_lo(sa, b1_, S[2]); S[3] = fmix_hi(sa, b1_, S[3]);
;         S[0] = fmix_lo(vv, kd0, S[0]); S[1] = fmix_hi(vv, kd0, S[1]); S[2] = fmix_lo(vv, kd1, S[2]); S[3] = fmix_hi(vv, kd1, S[3]);
;         float y = fmix_lo(S[0], r0_, 0.f); y = fmix_hi(S[1], r0_, y);
;         float y2 = fmix_lo(S[2], r1_, 0.f); y2 = fmix_hi(S[3], r1_, y2);
;         y += y2;
;         if (VAR == 0 && islat) {
;           y = row_sum16(y);
;           if (q == 0) yout[((size_t)dir * NL + row_of(t0 + uu)) * RWW + hh * 64 + vrow] = (h16)y;
;         }
;         if (VAR != 0) asm volatile("" :: "v"(y));
;         const int nstep = t0 + uu + RW_U < RW_NS ? t0 + uu + RW_U : RW_NS - 1;
;         if (VAR != 2) RW_LOAD(uu, nstep);
	global_load_dwordx4 v[184:187], v62, s[6:7]
	v_fma_mix_f32 v10, v18, v198, v14 op_sel_hi:[0,1,0]
	global_load_dwordx2 v[188:189], v62, s[6:7] offset:16
	v_fma_mix_f32 v11, v18, v198, v15 op_sel:[0,1,0] op_sel_hi:[0,1,0]
	global_load_dwordx4 v[190:193], v73, s[8:9]
	v_fma_mix_f32 v12, v18, v199, v16 op_sel_hi:[0,1,0]
	v_fma_mix_f32 v13, v18, v199, v17 op_sel:[0,1,0] op_sel_hi:[0,1,0]
	v_mov_b32_dpp v38, v36 row_newbcast:12 row_mask:0xf bank_mask:0xf
	v_fma_mix_f32 v18, v10, v210, 0 op_sel_hi:[0,1,0]
	v_fma_mix_f32 v14, v10, v204, v10 op_sel_hi:[0,1,0]
	v_fma_mix_f32 v18, v11, v210, v18 op_sel:[0,1,0] op_sel_hi:[0,1,0]
	v_fma_mix_f32 v15, v11, v204, v11 op_sel:[0,1,0] op_sel_hi:[0,1,0]
	v_fma_mix_f32 v18, v12, v211, v18 op_sel_hi:[0,1,0]
	v_fma_mix_f32 v16, v12, v205, v12 op_sel_hi:[0,1,0]
	v_fma_mix_f32 v18, v13, v211, v18 op_sel:[0,1,0] op_sel_hi:[0,1,0]
	v_fma_mix_f32 v17, v13, v205, v13 op_sel:[0,1,0] op_sel_hi:[0,1,0]
	v_fma_mix_f32 v14, v38, v206, v14 op_sel_hi:[1,1,0]
	v_fma_mix_f32 v15, v38, v206, v15 op_sel:[0,1,0] op_sel_hi:[1,1,0]
	v_add_f32_dpp v18, v18, v18 quad_perm:[1,0,3,2] row_mask:0xf bank_mask:0xf bound_ctrl:1
	v_fma_mix_f32 v16, v38, v207, v16 op_sel_hi:[1,1,0]
	v_fma_mix_f32 v17, v38, v207, v17 op_sel:[0,1,0] op_sel_hi:[1,1,0]
	v_add_f32_dpp v18, v18, v18 quad_perm:[2,3,0,1] row_mask:0xf bank_mask:0xf bound_ctrl:1
	v_fma_mix_f32 v31, v10, v202, 0 op_sel_hi:[0,1,0]
	v_fma_mix_f32 v31, v11, v202, v31 op_sel:[0,1,0] op_sel_hi:[0,1,0]
	v_add_f32_dpp v18, v18, v18 row_ror:4 row_mask:0xf bank_mask:0xf bound_ctrl:1
	v_fma_mix_f32 v31, v12, v203, v31 op_sel_hi:[0,1,0]
	v_fma_mix_f32 v31, v13, v203, v31 op_sel:[0,1,0] op_sel_hi:[0,1,0]
	v_add_f32_dpp v18, v18, v18 row_ror:8 row_mask:0xf bank_mask:0xf bound_ctrl:1
	s_waitcnt vmcnt(39)
	global_load_dwordx4 v[194:197], v63, s[6:7]
	v_fma_mix_f32 v10, v18, v208, v14 op_sel_hi:[0,1,0]
	global_load_dwordx2 v[198:199], v63, s[6:7] offset:16
	v_fma_mix_f32 v11, v18, v208, v15 op_sel:[0,1,0] op_sel_hi:[0,1,0]
	global_load_dwordx4 v[200:203], v73, s[8:9] offset:-4096
	v_fma_mix_f32 v12, v18, v209, v16 op_sel_hi:[0,1,0]
	v_fma_mix_f32 v13, v18, v209, v17 op_sel:[0,1,0] op_sel_hi:[0,1,0]
	v_mov_b32_dpp v38, v36 row_newbcast:13 row_mask:0xf bank_mask:0xf
	v_fma_mix_f32 v18, v10, v220, 0 op_sel_hi:[0,1,0]
	v_fma_mix_f32 v14, v10, v214, v10 op_sel_hi:[0,1,0]
	v_fma_mix_f32 v18, v11, v220, v18 op_sel:[0,1,0] op_sel_hi:[0,1,0]
	v_fma_mix_f32 v15, v11, v214, v11 op_sel:[0,1,0] op_sel_hi:[0,1,0]
	v_fma_mix_f32 v18, v12, v221, v18 op_sel_hi:[0,1,0]
	v_fma_mix_f32 v16, v12, v215, v12 op_sel_hi:[0,1,0]
	v_fma_mix_f32 v18, v13, v221, v18 op_sel:[0,1,0] op_sel_hi:[0,1,0]
	v_fma_mix_f32 v17, v13, v215, v13 op_sel:[0,1,0] op_sel_hi:[0,1,0]
	v_fma_mix_f32 v14, v38, v216, v14 op_sel_hi:[1,1,0]
	v_fma_mix_f32 v15, v38, v216, v15 op_sel:[0,1,0] op_sel_hi:[1,1,0]
	v_add_f32_dpp v18, v18, v18 quad_perm:[1,0,3,2] row_mask:0xf bank_mask:0xf bound_ctrl:1
	v_fma_mix_f32 v16, v38, v217, v16 op_sel_hi:[1,1,0]
	v_fma_mix_f32 v17, v38, v217, v17 op_sel:[0,1,0] op_sel_hi:[1,1,0]
	v_add_f32_dpp v18, v18, v18 quad_perm:[2,3,0,1] row_mask:0xf bank_mask:0xf bound_ctrl:1
	v_fma_mix_f32 v32, v10, v212, 0 op_sel_hi:[0,1,0]
	v_fma_mix_f32 v32, v11, v212, v32 op_sel:[0,1,0] op_sel_hi:[0,1,0]
	v_add_f32_dpp v18, v18, v18 row_ror:4 row_mask:0xf bank_mask:0xf bound_ctrl:1
	v_fma_mix_f32 v32, v12, v213, v32 op_sel_hi:[0,1,0]
	v_fma_mix_f32 v32, v13, v213, v32 op_sel:[0,1,0] op_sel_hi:[0,1,0]
	v_add_f32_dpp v18, v18, v18 row_ror:8 row_mask:0xf bank_mask:0xf bound_ctrl:1
	s_waitcnt vmcnt(39)
	global_load_dwordx4 v[204:207], v64, s[6:7]
	v_fma_mix_f32 v10, v18, v218, v14 op_sel_hi:[0,1,0]
	global_load_dwordx2 v[208:209], v64, s[6:7] offset:16
	v_fma_mix_f32 v11, v18, v218, v15 op_sel:[0,1,0] op_sel_hi:[0,1,0]
	global_load_dwordx4 v[210:213], v74, s[8:9]
	v_fma_mix_f32 v12, v18, v219, v16 op_sel_hi:[0,1,0]
	v_fma_mix_f32 v13, v18, v219, v17 op_sel:[0,1,0] op_sel_hi:[0,1,0]
	v_mov_b32_dpp v38, v36 row_newbcast:14 row_mask:0xf bank_mask:0xf
	v_fma_mix_f32 v18, v10, v230, 0 op_sel_hi:[0,1,0]
	v_fma_mix_f32 v14, v10, v224, v10 op_sel_hi:[0,1,0]
	v_fma_mix_f32 v18, v11, v230, v18 op_sel:[0,1,0] op_sel_hi:[0,1,0]
	v_fma_mix_f32 v15, v11, v224, v11 op_sel:[0,1,0] op_sel_hi:[0,1,0]
	v_fma_mix_f32 v18, v12, v231, v18 op_sel_hi:[0,1,0]
	v_fma_mix_f32 v16, v12, v225, v12 op_sel_hi:[0,1,0]
	v_fma_mix_f32 v18, v13, v231, v18 op_sel:[0,1,0] op_sel_hi:[0,1,0]
	v_fma_mix_f32 v17, v13, v225, v13 op_sel:[0,1,0] op_sel_hi:[0,1,0]
	v_fma_mix_f32 v14, v38, v226, v14 op_sel_hi:[1,1,0]
	v_fma_mix_f32 v15, v38, v226, v15 op_sel:[0,1,0] op_sel_hi:[1,1,0]
	v_add_f32_dpp v18, v18, v18 quad_perm:[1,0,3,2] row_mask:0xf bank_mask:0xf bound_ctrl:1
	v_fma_mix_f32 v16, v38, v227, v16 op_sel_hi:[1,1,0]
	v_fma_mix_f32 v17, v38, v227, v17 op_sel:[0,1,0] op_sel_hi:[1,1,0]
	v_add_f32_dpp v18, v18, v18 quad_perm:[2,3,0,1] row_mask:0xf bank_mask:0xf bound_ctrl:1
	v_fma_mix_f32 v33, v10, v222, 0 op_sel_hi:[0,1,0]
	v_fma_mix_f32 v33, v11, v222, v33 op_sel:[0,1,0] op_sel_hi:[0,1,0]
	v_add_f32_dpp v18, v18, v18 row_ror:4 row_mask:0xf bank_mask:0xf bound_ctrl:1
	v_fma_mix_f32 v33, v12, v223, v33 op_sel_hi:[0,1,0]
	v_fma_mix_f32 v33, v13, v223, v33 op_sel:[0,1,0] op_sel_hi:[0,1,0]
	v_add_f32_dpp v18, v18, v18 row_ror:8 row_mask:0xf bank_mask:0xf bound_ctrl:1
	s_waitcnt vmcnt(39)
; __device__ __forceinline__ float row_sum16(float v) { v += __shfl_xor(v, 1); v += __shfl_xor(v, 2); v += __shfl_xor(v, 4); v += __shfl_xor(v, 8); return v; }
; __device__ __forceinline__ float row_sum16(float v) { v += dppf<0xB1>(v); v += dppf<0x4E>(v); v += dppf<0x124>(v); v += dppf<0x128>(v); return v; }
; #define RW_LOAD(slot, step) do { const size_t ro_ = (size_t)row_of(step) * RWW; \
;       s_ok[slot] = *(const h16x8*)((p_rec + ro_ * 3) + urec); s_b[slot] = *(const h16x4*)((p_rec + ro_ * 3) + urec + 8); \
;       s_kr[slot] = *(const h16x8*)((p_sh + ro_ * 2) + ush); s_v[slot] = (p_v + ro_)[uvoff]; } while (0)
; template <int VAR>
; __device__ __forceinline__ void ph_rw_scan(const Params& P) {
;     ...
;         const float vv = (float)s_v[uu];
;         const u32x4 p_ok = __builtin_bit_cast(u32x4, s_ok[uu]), p_kr = __builtin_bit_cast(u32x4, s_kr[uu]);
;         const u32x2 p_bb = __builtin_bit_cast(u32x2, s_b[uu]);
;         const unsigned om0 = p_ok[0], om1 = p_ok[1], kd0 = p_ok[2], kd1 = p_ok[3];
;         const unsigned kk0 = p_kr[0], kk1 = p_kr[1], r0_ = p_kr[2], r1_ = p_kr[3];
;         const unsigned b0_ = p_bb[0], b1_ = p_bb[1];
;         float sa = fmix_lo(S[0], kk0, 0.f); sa = fmix_hi(S[1], kk0, sa);
;         float sb = fmix_lo(S[2], kk1, 0.f); sb = fmix_hi(S[3], kk1, sb);
;         sa = row_sum16(sa + sb);
;         S[0] = fmix_lo(S[0], om0, S[0]); S[1] = fmix_hi(S[1], om0, S[1]); S[2] = fmix_lo(S[2], om1, S[2]); S[3] = fmix_hi(S[3], om1, S[3]);
;         S[0] = fmix_lo(sa, b0_, S[0]); S[1] = fmix_hi(sa, b0_, S[1]); S[2] = fmix_lo(sa, b1_, S[2]); S[3] = fmix_hi(sa, b1_, S[3]);
;         S[0] = fmix_lo(vv, kd0, S[0]); S[1] = fmix_hi(vv, kd0, S[1]); S[2] = fmix_lo(vv, kd1, S[2]); S[3] = fmix_hi(vv, kd1, S[3]);
;         float y = fmix_lo(S[0], r0_, 0.f); y = fmix_hi(S[1], r0_, y);
;         float y2 = fmix_lo(S[2], r1_, 0.f); y2 = fmix_hi(S[3], r1_, y2);
;         y += y2;
;         if (VAR == 0 && islat) {
;           y = row_sum16(y);
;           if (q == 0) yout[((size_t)dir * NL + row_of(t0 + uu)) * RWW + hh * 64 + vrow] = (h16)y;
;         }
;         if (VAR != 0) asm volatile("" :: "v"(y));
;         const int nstep = t0 + uu + RW_U < RW_NS ? t0 + uu + RW_U : RW_NS - 1;
;         if (VAR != 2) RW_LOAD(uu, nstep);
	global_load_dwordx4 v[214:217], v65, s[6:7]
	v_fma_mix_f32 v10, v18, v228, v14 op_sel_hi:[0,1,0]
	global_load_dwordx2 v[218:219], v65, s[6:7] offset:16
	v_fma_mix_f32 v11, v18, v228, v15 op_sel:[0,1,0] op_sel_hi:[0,1,0]
	global_load_dwordx4 v[220:223], v74, s[8:9] offset:-4096
	v_fma_mix_f32 v12, v18, v229, v16 op_sel_hi:[0,1,0]
	v_fma_mix_f32 v13, v18, v229, v17 op_sel:[0,1,0] op_sel_hi:[0,1,0]
	v_mov_b32_dpp v38, v36 row_newbcast:15 row_mask:0xf bank_mask:0xf
	v_fma_mix_f32 v18, v10, v240, 0 op_sel_hi:[0,1,0]
	v_fma_mix_f32 v14, v10, v234, v10 op_sel_hi:[0,1,0]
	v_fma_mix_f32 v18, v11, v240, v18 op_sel:[0,1,0] op_sel_hi:[0,1,0]
	v_fma_mix_f32 v15, v11, v234, v11 op_sel:[0,1,0] op_sel_hi:[0,1,0]
	v_fma_mix_f32 v18, v12, v241, v18 op_sel_hi:[0,1,0]
	v_fma_mix_f32 v16, v12, v235, v12 op_sel_hi:[0,1,0]
	v_fma_mix_f32 v18, v13, v241, v18 op_sel:[0,1,0] op_sel_hi:[0,1,0]
	v_fma_mix_f32 v17, v13, v235, v13 op_sel:[0,1,0] op_sel_hi:[0,1,0]
	v_fma_mix_f32 v14, v38, v236, v14 op_sel_hi:[1,1,0]
	v_fma_mix_f32 v15, v38, v236, v15 op_sel:[0,1,0] op_sel_hi:[1,1,0]
	v_add_f32_dpp v18, v18, v18 quad_perm:[1,0,3,2] row_mask:0xf bank_mask:0xf bound_ctrl:1
	v_fma_mix_f32 v16, v38, v237, v16 op_sel_hi:[1,1,0]
	v_fma_mix_f32 v17, v38, v237, v17 op_sel:[0,1,0] op_sel_hi:[1,1,0]
	v_add_f32_dpp v18, v18, v18 quad_perm:[2,3,0,1] row_mask:0xf bank_mask:0xf bound_ctrl:1
	v_fma_mix_f32 v34, v10, v232, 0 op_sel_hi:[0,1,0]
	v_fma_mix_f32 v34, v11, v232, v34 op_sel:[0,1,0] op_sel_hi:[0,1,0]
	v_add_f32_dpp v18, v18, v18 row_ror:4 row_mask:0xf bank_mask:0xf bound_ctrl:1
	v_fma_mix_f32 v34, v12, v233, v34 op_sel_hi:[0,1,0]
	v_fma_mix_f32 v34, v13, v233, v34 op_sel:[0,1,0] op_sel_hi:[0,1,0]
	v_add_f32_dpp v18, v18, v18 row_ror:8 row_mask:0xf bank_mask:0xf bound_ctrl:1
	s_waitcnt vmcnt(39)
	global_load_dwordx4 v[224:227], v66, s[6:7]
	v_fma_mix_f32 v10, v18, v238, v14 op_sel_hi:[0,1,0]
	global_load_dwordx2 v[228:229], v66, s[6:7] offset:16
	v_fma_mix_f32 v11, v18, v238, v15 op_sel:[0,1,0] op_sel_hi:[0,1,0]
	global_load_dwordx4 v[230:233], v75, s[8:9]
	v_fma_mix_f32 v12, v18, v239, v16 op_sel_hi:[0,1,0]
	v_fma_mix_f32 v13, v18, v239, v17 op_sel:[0,1,0] op_sel_hi:[0,1,0]
	v_mov_b32_e32 v36, v37
	s_add_u32 s3, s3, 1
	s_cmp_lt_u32 s3, 0x410
	s_cbranch_scc1 .Lscan_loop_d1
	v_fma_mix_f32 v35, v10, v242, 0 op_sel_hi:[0,1,0]
	v_fma_mix_f32 v35, v11, v242, v35 op_sel:[0,1,0] op_sel_hi:[0,1,0]
	v_fma_mix_f32 v35, v12, v243, v35 op_sel_hi:[0,1,0]
	v_fma_mix_f32 v35, v13, v243, v35 op_sel:[0,1,0] op_sel_hi:[0,1,0]
	s_nop 1
	v_add_f32_dpp v20, v20, v20 row_ror:8 row_mask:0xf bank_mask:0xf bound_ctrl:1
	v_add_f32_dpp v21, v21, v21 row_ror:8 row_mask:0xf bank_mask:0xf bound_ctrl:1
	v_add_f32_dpp v22, v22, v22 row_ror:8 row_mask:0xf bank_mask:0xf bound_ctrl:1
	v_add_f32_dpp v23, v23, v23 row_ror:8 row_mask:0xf bank_mask:0xf bound_ctrl:1
	v_add_f32_dpp v24, v24, v24 row_ror:8 row_mask:0xf bank_mask:0xf bound_ctrl:1
	v_add_f32_dpp v25, v25, v25 row_ror:8 row_mask:0xf bank_mask:0xf bound_ctrl:1
	v_add_f32_dpp v26, v26, v26 row_ror:8 row_mask:0xf bank_mask:0xf bound_ctrl:1
	v_add_f32_dpp v27, v27, v27 row_ror:8 row_mask:0xf bank_mask:0xf bound_ctrl:1
	v_add_f32_dpp v20, v28, v28 row_ror:8 row_mask:0xf bank_mask:0xc bound_ctrl:1
	v_add_f32_dpp v21, v29, v29 row_ror:8 row_mask:0xf bank_mask:0xc bound_ctrl:1
	v_add_f32_dpp v22, v30, v30 row_ror:8 row_mask:0xf bank_mask:0xc bound_ctrl:1
	v_add_f32_dpp v23, v31, v31 row_ror:8 row_mask:0xf bank_mask:0xc bound_ctrl:1
	v_add_f32_dpp v24, v32, v32 row_ror:8 row_mask:0xf bank_mask:0xc bound_ctrl:1
	v_add_f32_dpp v25, v33, v33 row_ror:8 row_mask:0xf bank_mask:0xc bound_ctrl:1
	v_add_f32_dpp v26, v34, v34 row_ror:8 row_mask:0xf bank_mask:0xc bound_ctrl:1
	v_add_f32_dpp v27, v35, v35 row_ror:8 row_mask:0xf bank_mask:0xc bound_ctrl:1
	v_add_f32_dpp v20, v20, v20 row_half_mirror row_mask:0xf bank_mask:0xf bound_ctrl:1
	v_add_f32_dpp v21, v21, v21 row_half_mirror row_mask:0xf bank_mask:0xf bound_ctrl:1
	v_add_f32_dpp v22, v22, v22 row_half_mirror row_mask:0xf bank_mask:0xf bound_ctrl:1
	v_add_f32_dpp v23, v23, v23 row_half_mirror row_mask:0xf bank_mask:0xf bound_ctrl:1
	v_add_f32_dpp v20, v24, v24 row_half_mirror row_mask:0xf bank_mask:0xa bound_ctrl:1
	v_add_f32_dpp v21, v25, v25 row_half_mirror row_mask:0xf bank_mask:0xa bound_ctrl:1
	v_add_f32_dpp v22, v26, v26 row_half_mirror row_mask:0xf bank_mask:0xa bound_ctrl:1
	v_add_f32_dpp v23, v27, v27 row_half_mirror row_mask:0xf bank_mask:0xa bound_ctrl:1
	v_add_f32_dpp v20, v20, v20 quad_perm:[1,0,3,2] row_mask:0xf bank_mask:0xf bound_ctrl:1
	v_add_f32_dpp v21, v21, v21 quad_perm:[1,0,3,2] row_mask:0xf bank_mask:0xf bound_ctrl:1
	v_add_f32_dpp v22, v22, v22 quad_perm:[1,0,3,2] row_mask:0xf bank_mask:0xf bound_ctrl:1
	v_add_f32_dpp v23, v23, v23 quad_perm:[1,0,3,2] row_mask:0xf bank_mask:0xf bound_ctrl:1
	v_add_f32_dpp v20, v20, v20 quad_perm:[2,3,0,1] row_mask:0xf bank_mask:0xf bound_ctrl:1
	v_add_f32_dpp v21, v21, v21 quad_perm:[2,3,0,1] row_mask:0xf bank_mask:0xf bound_ctrl:1
	v_add_f32_dpp v22, v22, v22 quad_perm:[2,3,0,1] row_mask:0xf bank_mask:0xf bound_ctrl:1
	v_add_f32_dpp v23, v23, v23 quad_perm:[2,3,0,1] row_mask:0xf bank_mask:0xf bound_ctrl:1
	v_cndmask_b32_e64 v20, v20, v21, s[20:21]
	v_cndmask_b32_e64 v20, v20, v22, s[22:23]
	v_cndmask_b32_e64 v20, v20, v23, s[24:25]
	v_cvt_f16_f32_e32 v81, v20
	global_store_short v80, v81, s[12:13]
	s_sub_u32 s12, s12, 0x8000
	s_subb_u32 s13, s13, 0
	s_waitcnt vmcnt(0)
	s_branch .Lscan_next
